# SwiGLU epilogue: out=(u*g)*rcp((1+exp(-rs*g))*ms) refactor (fewer f32 VALU ops, same kinds) + in-place packed slot reduction
# speedup vs baseline: 1.0135x; 1.0064x over previous
.LBB0_165:
	v_ashrrev_i32_e32 v153, 31, v152
	v_lshlrev_b64 v[154:155], 6, v[152:153]
	v_lshl_add_u64 v[170:171], s[74:75], 0, v[154:155]
	s_waitcnt lgkmcnt(0)
	global_load_dwordx4 v[154:157], v[170:171], off
	global_load_dwordx4 v[162:165], v[170:171], off offset:16
	global_load_dwordx4 v[166:169], v[170:171], off offset:32
	s_nop 0
	global_load_dwordx4 v[170:173], v[170:171], off offset:48
	v_mov_b32_e32 v174, v124
	v_mov_b32_e32 v175, v116
	v_mov_b32_e32 v116, v125
	v_mov_b32_e32 v124, v126
	v_mov_b32_e32 v125, v118
	v_mov_b32_e32 v118, v127
	v_mov_b32_e32 v126, v120
	v_mov_b32_e32 v127, v112
	v_mov_b32_e32 v112, v121
	v_mov_b32_e32 v176, v122
	v_mov_b32_e32 v177, v114
	v_mov_b32_e32 v114, v123
	s_lshl_b32 s24, s24, 7
	v_mov_b64_e32 v[120:121], s[72:73]
	s_ashr_i32 s25, s24, 31
	v_mad_i64_i32 v[122:123], s[26:27], v152, s51, v[120:121]
	s_lshl_b64 s[24:25], s[24:25], 1
	v_lshl_add_u64 v[122:123], v[122:123], 0, s[24:25]
	v_lshl_add_u64 v[122:123], v[122:123], 0, s[6:7]
	s_waitcnt vmcnt(2)
	v_pk_add_f32 v[154:155], v[154:155], v[156:157]
	v_pk_add_f32 v[162:163], v[162:163], v[164:165]
	s_waitcnt vmcnt(0)
	v_pk_add_f32 v[166:167], v[166:167], v[168:169]
	v_pk_add_f32 v[170:171], v[170:171], v[172:173]
	v_pk_add_f32 v[154:155], v[154:155], v[162:163]
	v_pk_add_f32 v[166:167], v[166:167], v[170:171]
	v_mul_f32_e32 v116, v116, v117
	v_mul_f32_e32 v124, v124, v125
	v_mul_f32_e32 v118, v118, v119
	v_mul_f32_e32 v126, v126, v127
	v_pk_add_f32 v[154:155], v[154:155], v[166:167]
	v_mul_f32_e32 v174, v174, v175
	v_mul_f32_e32 v112, v112, v113
	v_mul_f32_e32 v176, v176, v177
	v_mul_f32_e32 v114, v114, v115
	v_add_f32_e32 v154, v154, v155
	v_fmamk_f32 v154, v154, 0x3a800000, v160
	v_rsq_f32_e32 v155, v154
	s_nop 0
	v_mul_f32_e32 v155, 0xbfb8aa3b, v155
	v_mul_f32_e32 v117, v155, v117
	v_mul_f32_e32 v125, v155, v125
	v_mul_f32_e32 v119, v155, v119
	v_mul_f32_e32 v127, v155, v127
	v_mul_f32_e32 v175, v155, v175
	v_mul_f32_e32 v113, v155, v113
	v_mul_f32_e32 v177, v155, v177
	v_mul_f32_e32 v115, v155, v115
	v_exp_f32_e32 v117, v117
	v_exp_f32_e32 v125, v125
	v_exp_f32_e32 v119, v119
	v_exp_f32_e32 v127, v127
	v_exp_f32_e32 v175, v175
	v_exp_f32_e32 v113, v113
	v_exp_f32_e32 v177, v177
	v_exp_f32_e32 v115, v115
	v_fma_f32 v117, v117, v154, v154
	v_fma_f32 v125, v125, v154, v154
	v_fma_f32 v119, v119, v154, v154
	v_fma_f32 v127, v127, v154, v154
	v_fma_f32 v175, v175, v154, v154
	v_fma_f32 v113, v113, v154, v154
	v_fma_f32 v177, v177, v154, v154
	v_fma_f32 v115, v115, v154, v154
	v_rcp_f32_e32 v117, v117
	v_rcp_f32_e32 v125, v125
	v_rcp_f32_e32 v119, v119
	v_rcp_f32_e32 v127, v127
	v_rcp_f32_e32 v175, v175
	v_rcp_f32_e32 v113, v113
	v_rcp_f32_e32 v177, v177
	v_rcp_f32_e32 v115, v115
	v_mul_f32_e32 v116, v116, v117
	v_mul_f32_e32 v124, v124, v125
	v_mul_f32_e32 v118, v118, v119
	v_mul_f32_e32 v126, v126, v127
	v_mul_f32_e32 v174, v174, v175
	v_mul_f32_e32 v112, v112, v113
	v_mul_f32_e32 v176, v176, v177
	v_mul_f32_e32 v114, v114, v115
	v_cvt_pk_bf16_f32 v113, v124, v118
	v_cvt_pk_bf16_f32 v115, v176, v114
	v_cvt_pk_bf16_f32 v114, v126, v112
	v_cvt_pk_bf16_f32 v112, v174, v116
	v_or_b32_e32 v126, 16, v152
	v_lshl_add_u64 v[116:117], v[122:123], 0, v[136:137]
	v_ashrrev_i32_e32 v127, 31, v126
	global_store_dwordx4 v[116:117], v[112:115], off
	v_mov_b32_e32 v162, v108
	v_mov_b32_e32 v163, v100
	v_lshlrev_b64 v[112:113], 6, v[126:127]
	v_lshl_add_u64 v[154:155], s[74:75], 0, v[112:113]
	global_load_dwordx4 v[112:115], v[154:155], off
	global_load_dwordx4 v[116:119], v[154:155], off offset:16
	global_load_dwordx4 v[122:125], v[154:155], off offset:32
	s_nop 0
	global_load_dwordx4 v[154:157], v[154:155], off offset:48
	v_mov_b32_e32 v100, v109
	v_mov_b32_e32 v108, v110
	v_mov_b32_e32 v109, v102
	v_mov_b32_e32 v102, v111
	v_mov_b32_e32 v110, v104
	v_mov_b32_e32 v111, v96
	v_mov_b32_e32 v96, v105
	v_mov_b32_e32 v104, v106
	v_mov_b32_e32 v105, v98
	v_mov_b32_e32 v98, v107
	s_waitcnt vmcnt(2)
	v_pk_add_f32 v[112:113], v[112:113], v[114:115]
	v_pk_add_f32 v[116:117], v[116:117], v[118:119]
	s_waitcnt vmcnt(0)
	v_pk_add_f32 v[122:123], v[122:123], v[124:125]
	v_pk_add_f32 v[154:155], v[154:155], v[156:157]
	v_pk_add_f32 v[112:113], v[112:113], v[116:117]
	v_pk_add_f32 v[122:123], v[122:123], v[154:155]
	v_mul_f32_e32 v100, v100, v101
	v_mul_f32_e32 v108, v108, v109
	v_mul_f32_e32 v162, v162, v163
	v_mul_f32_e32 v102, v102, v103
	v_pk_add_f32 v[112:113], v[112:113], v[122:123]
	v_mul_f32_e32 v110, v110, v111
	v_mul_f32_e32 v96, v96, v97
	v_mul_f32_e32 v104, v104, v105
	v_mul_f32_e32 v98, v98, v99
	v_add_f32_e32 v112, v112, v113
	v_fmamk_f32 v112, v112, 0x3a800000, v160
	v_rsq_f32_e32 v113, v112
	s_nop 0
	v_mul_f32_e32 v113, 0xbfb8aa3b, v113
	v_mul_f32_e32 v101, v113, v101
	v_mul_f32_e32 v109, v113, v109
	v_mul_f32_e32 v163, v113, v163
	v_mul_f32_e32 v103, v113, v103
	v_mul_f32_e32 v111, v113, v111
	v_mul_f32_e32 v97, v113, v97
	v_mul_f32_e32 v105, v113, v105
	v_mul_f32_e32 v99, v113, v99
	v_exp_f32_e32 v101, v101
	v_exp_f32_e32 v109, v109
	v_exp_f32_e32 v163, v163
	v_exp_f32_e32 v103, v103
	v_exp_f32_e32 v111, v111
	v_exp_f32_e32 v97, v97
	v_exp_f32_e32 v105, v105
	v_exp_f32_e32 v99, v99
	v_fma_f32 v101, v101, v112, v112
	v_fma_f32 v109, v109, v112, v112
	v_fma_f32 v163, v163, v112, v112
	v_fma_f32 v103, v103, v112, v112
	v_fma_f32 v111, v111, v112, v112
	v_fma_f32 v97, v97, v112, v112
	v_fma_f32 v105, v105, v112, v112
	v_fma_f32 v99, v99, v112, v112
	v_rcp_f32_e32 v101, v101
	v_rcp_f32_e32 v109, v109
	v_rcp_f32_e32 v163, v163
	v_rcp_f32_e32 v103, v103
	v_rcp_f32_e32 v111, v111
	v_rcp_f32_e32 v97, v97
	v_rcp_f32_e32 v105, v105
	v_rcp_f32_e32 v99, v99
	v_mul_f32_e32 v100, v100, v101
	v_mul_f32_e32 v108, v108, v109
	v_mul_f32_e32 v162, v162, v163
	v_mul_f32_e32 v102, v102, v103
	v_mul_f32_e32 v110, v110, v111
	v_mul_f32_e32 v96, v96, v97
	v_mul_f32_e32 v104, v104, v105
	v_mul_f32_e32 v98, v98, v99
	v_cvt_pk_bf16_f32 v97, v108, v102
	v_cvt_pk_bf16_f32 v99, v104, v98
	v_cvt_pk_bf16_f32 v98, v110, v96
	v_cvt_pk_bf16_f32 v96, v162, v100
	v_mad_i64_i32 v[112:113], s[26:27], v126, s51, v[120:121]
	v_lshl_add_u64 v[112:113], v[112:113], 0, s[24:25]
	v_lshl_add_u64 v[100:101], v[112:113], 0, s[6:7]
	v_or_b32_e32 v112, 32, v152
	v_lshl_add_u64 v[100:101], v[100:101], 0, v[136:137]
	v_ashrrev_i32_e32 v113, 31, v112
	global_store_dwordx4 v[100:101], v[96:99], off
	v_mov_b32_e32 v114, v92
	v_mov_b32_e32 v92, v94
	v_lshlrev_b64 v[96:97], 6, v[112:113]
	v_lshl_add_u64 v[108:109], s[74:75], 0, v[96:97]
	global_load_dwordx4 v[96:99], v[108:109], off
	global_load_dwordx4 v[100:103], v[108:109], off offset:16
	global_load_dwordx4 v[104:107], v[108:109], off offset:32
	s_nop 0
	global_load_dwordx4 v[108:111], v[108:109], off offset:48
	v_mov_b32_e32 v94, v80
	v_mov_b32_e32 v80, v82
	v_mov_b32_e32 v115, v88
	v_mov_b32_e32 v88, v93
	v_mov_b32_e32 v93, v90
	v_mov_b32_e32 v90, v95
	v_mov_b32_e32 v95, v84
	v_mov_b32_e32 v84, v81
	v_mov_b32_e32 v81, v86
	v_mov_b32_e32 v86, v83
	s_waitcnt vmcnt(2)
	v_pk_add_f32 v[96:97], v[96:97], v[98:99]
	v_pk_add_f32 v[100:101], v[100:101], v[102:103]
	s_waitcnt vmcnt(0)
	v_pk_add_f32 v[104:105], v[104:105], v[106:107]
	v_pk_add_f32 v[108:109], v[108:109], v[110:111]
	v_pk_add_f32 v[96:97], v[96:97], v[100:101]
	v_pk_add_f32 v[104:105], v[104:105], v[108:109]
	v_mul_f32_e32 v114, v114, v115
	v_mul_f32_e32 v88, v88, v89
	v_mul_f32_e32 v92, v92, v93
	v_mul_f32_e32 v90, v90, v91
	v_pk_add_f32 v[96:97], v[96:97], v[104:105]
	v_mul_f32_e32 v94, v94, v95
	v_mul_f32_e32 v84, v84, v85
	v_mul_f32_e32 v80, v80, v81
	v_mul_f32_e32 v86, v86, v87
	v_add_f32_e32 v96, v96, v97
	v_fmamk_f32 v96, v96, 0x3a800000, v160
	v_rsq_f32_e32 v97, v96
	s_nop 0
	v_mul_f32_e32 v97, 0xbfb8aa3b, v97
	v_mul_f32_e32 v115, v97, v115
	v_mul_f32_e32 v89, v97, v89
	v_mul_f32_e32 v93, v97, v93
	v_mul_f32_e32 v91, v97, v91
	v_mul_f32_e32 v95, v97, v95
	v_mul_f32_e32 v85, v97, v85
	v_mul_f32_e32 v81, v97, v81
	v_mul_f32_e32 v87, v97, v87
	v_exp_f32_e32 v115, v115
	v_exp_f32_e32 v89, v89
	v_exp_f32_e32 v93, v93
	v_exp_f32_e32 v91, v91
	v_exp_f32_e32 v95, v95
	v_exp_f32_e32 v85, v85
	v_exp_f32_e32 v81, v81
	v_exp_f32_e32 v87, v87
	v_fma_f32 v115, v115, v96, v96
	v_fma_f32 v89, v89, v96, v96
	v_fma_f32 v93, v93, v96, v96
	v_fma_f32 v91, v91, v96, v96
	v_fma_f32 v95, v95, v96, v96
	v_fma_f32 v85, v85, v96, v96
	v_fma_f32 v81, v81, v96, v96
	v_fma_f32 v87, v87, v96, v96
	v_rcp_f32_e32 v115, v115
	v_rcp_f32_e32 v89, v89
	v_rcp_f32_e32 v93, v93
	v_rcp_f32_e32 v91, v91
	v_rcp_f32_e32 v95, v95
	v_rcp_f32_e32 v85, v85
	v_rcp_f32_e32 v81, v81
	v_rcp_f32_e32 v87, v87
	v_mul_f32_e32 v114, v114, v115
	v_mul_f32_e32 v88, v88, v89
	v_mul_f32_e32 v92, v92, v93
	v_mul_f32_e32 v90, v90, v91
	v_mul_f32_e32 v94, v94, v95
	v_mul_f32_e32 v84, v84, v85
	v_mul_f32_e32 v80, v80, v81
	v_mul_f32_e32 v86, v86, v87
	v_cvt_pk_bf16_f32 v81, v92, v90
	v_cvt_pk_bf16_f32 v82, v94, v84
	v_cvt_pk_bf16_f32 v83, v80, v86
	v_cvt_pk_bf16_f32 v80, v114, v88
	v_mad_i64_i32 v[96:97], s[26:27], v112, s51, v[120:121]
	v_lshl_add_u64 v[84:85], v[96:97], 0, s[24:25]
	v_lshl_add_u64 v[84:85], v[84:85], 0, s[6:7]
	v_or_b32_e32 v96, 48, v152
	v_lshl_add_u64 v[84:85], v[84:85], 0, v[136:137]
	v_ashrrev_i32_e32 v97, 31, v96
	global_store_dwordx4 v[84:85], v[80:83], off
	v_mov_b32_e32 v98, v76
	v_mov_b32_e32 v99, v72
	v_lshlrev_b64 v[80:81], 6, v[96:97]
	v_lshl_add_u64 v[92:93], s[74:75], 0, v[80:81]
	global_load_dwordx4 v[80:83], v[92:93], off
	global_load_dwordx4 v[84:87], v[92:93], off offset:16
	global_load_dwordx4 v[88:91], v[92:93], off offset:32
	s_nop 0
	global_load_dwordx4 v[92:95], v[92:93], off offset:48
	v_mov_b32_e32 v72, v77
	v_mov_b32_e32 v76, v78
	v_mov_b32_e32 v77, v74
	v_mov_b32_e32 v74, v79
	v_mov_b32_e32 v78, v64
	v_mov_b32_e32 v79, v68
	v_mov_b32_e32 v68, v65
	s_waitcnt vmcnt(2)
	v_pk_add_f32 v[80:81], v[80:81], v[82:83]
	v_pk_add_f32 v[84:85], v[84:85], v[86:87]
	s_waitcnt vmcnt(0)
	v_pk_add_f32 v[88:89], v[88:89], v[90:91]
	v_pk_add_f32 v[92:93], v[92:93], v[94:95]
	v_pk_add_f32 v[80:81], v[80:81], v[84:85]
	v_pk_add_f32 v[88:89], v[88:89], v[92:93]
	v_mul_f32_e32 v98, v98, v99
	v_mul_f32_e32 v72, v72, v73
	v_mul_f32_e32 v76, v76, v77
	v_mul_f32_e32 v68, v68, v69
	v_pk_add_f32 v[80:81], v[80:81], v[88:89]
	v_mul_f32_e32 v66, v66, v70
	v_mul_f32_e32 v74, v74, v75
	v_mul_f32_e32 v78, v78, v79
	v_mul_f32_e32 v67, v67, v71
	v_add_f32_e32 v80, v80, v81
	v_fmamk_f32 v80, v80, 0x3a800000, v160
	v_rsq_f32_e32 v81, v80
	s_nop 0
	v_mul_f32_e32 v81, 0xbfb8aa3b, v81
	v_mul_f32_e32 v99, v81, v99
	v_mul_f32_e32 v73, v81, v73
	v_mul_f32_e32 v77, v81, v77
	v_mul_f32_e32 v69, v81, v69
	v_mul_f32_e32 v70, v81, v70
	v_mul_f32_e32 v75, v81, v75
	v_mul_f32_e32 v79, v81, v79
	v_mul_f32_e32 v71, v81, v71
	v_exp_f32_e32 v99, v99
	v_exp_f32_e32 v73, v73
	v_exp_f32_e32 v77, v77
	v_exp_f32_e32 v69, v69
	v_exp_f32_e32 v70, v70
	v_exp_f32_e32 v75, v75
	v_exp_f32_e32 v79, v79
	v_exp_f32_e32 v71, v71
	v_fma_f32 v99, v99, v80, v80
	v_fma_f32 v73, v73, v80, v80
	v_fma_f32 v77, v77, v80, v80
	v_fma_f32 v69, v69, v80, v80
	v_fma_f32 v70, v70, v80, v80
	v_fma_f32 v75, v75, v80, v80
	v_fma_f32 v79, v79, v80, v80
	v_fma_f32 v71, v71, v80, v80
	v_rcp_f32_e32 v99, v99
	v_rcp_f32_e32 v73, v73
	v_rcp_f32_e32 v77, v77
	v_rcp_f32_e32 v69, v69
	v_rcp_f32_e32 v70, v70
	v_rcp_f32_e32 v75, v75
	v_rcp_f32_e32 v79, v79
	v_rcp_f32_e32 v71, v71
	v_mul_f32_e32 v98, v98, v99
	v_mul_f32_e32 v72, v72, v73
	v_mul_f32_e32 v76, v76, v77
	v_mul_f32_e32 v68, v68, v69
	v_mul_f32_e32 v66, v66, v70
	v_mul_f32_e32 v74, v74, v75
	v_mul_f32_e32 v78, v78, v79
	v_mul_f32_e32 v67, v67, v71
	v_cvt_pk_bf16_f32 v64, v98, v72
	v_cvt_pk_bf16_f32 v65, v76, v74
	v_cvt_pk_bf16_f32 v67, v66, v67
	v_cvt_pk_bf16_f32 v66, v78, v68
	v_mad_i64_i32 v[68:69], s[26:27], v96, s51, v[120:121]
	v_lshl_add_u64 v[68:69], v[68:69], 0, s[24:25]
	v_lshl_add_u64 v[68:69], v[68:69], 0, s[6:7]
	v_add_u32_e32 v80, 0x80, v152
	v_lshl_add_u64 v[68:69], v[68:69], 0, v[136:137]
	v_ashrrev_i32_e32 v81, 31, v80
	global_store_dwordx4 v[68:69], v[64:67], off
	v_mov_b32_e32 v82, v60
	v_mov_b32_e32 v83, v56
	v_lshlrev_b64 v[64:65], 6, v[80:81]
	v_lshl_add_u64 v[76:77], s[74:75], 0, v[64:65]
	global_load_dwordx4 v[64:67], v[76:77], off
	global_load_dwordx4 v[68:71], v[76:77], off offset:16
	global_load_dwordx4 v[72:75], v[76:77], off offset:32
	s_nop 0
	global_load_dwordx4 v[76:79], v[76:77], off offset:48
	v_mov_b32_e32 v56, v61
	v_mov_b32_e32 v60, v62
	v_mov_b32_e32 v61, v58
	v_mov_b32_e32 v58, v63
	v_mov_b32_e32 v62, v48
	v_mov_b32_e32 v63, v52
	v_mov_b32_e32 v52, v49
	s_waitcnt vmcnt(2)
	v_pk_add_f32 v[64:65], v[64:65], v[66:67]
	v_pk_add_f32 v[68:69], v[68:69], v[70:71]
	s_waitcnt vmcnt(0)
	v_pk_add_f32 v[72:73], v[72:73], v[74:75]
	v_pk_add_f32 v[76:77], v[76:77], v[78:79]
	v_pk_add_f32 v[64:65], v[64:65], v[68:69]
	v_pk_add_f32 v[72:73], v[72:73], v[76:77]
	v_mul_f32_e32 v82, v82, v83
	v_mul_f32_e32 v56, v56, v57
	v_mul_f32_e32 v60, v60, v61
	v_mul_f32_e32 v52, v52, v53
	v_pk_add_f32 v[64:65], v[64:65], v[72:73]
	v_mul_f32_e32 v50, v50, v54
	v_mul_f32_e32 v58, v58, v59
	v_mul_f32_e32 v62, v62, v63
	v_mul_f32_e32 v51, v51, v55
	v_add_f32_e32 v64, v64, v65
	v_fmamk_f32 v64, v64, 0x3a800000, v160
	v_rsq_f32_e32 v65, v64
	s_nop 0
	v_mul_f32_e32 v65, 0xbfb8aa3b, v65
	v_mul_f32_e32 v83, v65, v83
	v_mul_f32_e32 v57, v65, v57
	v_mul_f32_e32 v61, v65, v61
	v_mul_f32_e32 v53, v65, v53
	v_mul_f32_e32 v54, v65, v54
	v_mul_f32_e32 v59, v65, v59
	v_mul_f32_e32 v63, v65, v63
	v_mul_f32_e32 v55, v65, v55
	v_exp_f32_e32 v83, v83
	v_exp_f32_e32 v57, v57
	v_exp_f32_e32 v61, v61
	v_exp_f32_e32 v53, v53
	v_exp_f32_e32 v54, v54
	v_exp_f32_e32 v59, v59
	v_exp_f32_e32 v63, v63
	v_exp_f32_e32 v55, v55
	v_fma_f32 v83, v83, v64, v64
	v_fma_f32 v57, v57, v64, v64
	v_fma_f32 v61, v61, v64, v64
	v_fma_f32 v53, v53, v64, v64
	v_fma_f32 v54, v54, v64, v64
	v_fma_f32 v59, v59, v64, v64
	v_fma_f32 v63, v63, v64, v64
	v_fma_f32 v55, v55, v64, v64
	v_rcp_f32_e32 v83, v83
	v_rcp_f32_e32 v57, v57
	v_rcp_f32_e32 v61, v61
	v_rcp_f32_e32 v53, v53
	v_rcp_f32_e32 v54, v54
	v_rcp_f32_e32 v59, v59
	v_rcp_f32_e32 v63, v63
	v_rcp_f32_e32 v55, v55
	v_mul_f32_e32 v82, v82, v83
	v_mul_f32_e32 v56, v56, v57
	v_mul_f32_e32 v60, v60, v61
	v_mul_f32_e32 v52, v52, v53
	v_mul_f32_e32 v50, v50, v54
	v_mul_f32_e32 v58, v58, v59
	v_mul_f32_e32 v62, v62, v63
	v_mul_f32_e32 v51, v51, v55
	v_cvt_pk_bf16_f32 v48, v82, v56
	v_cvt_pk_bf16_f32 v49, v60, v58
	v_cvt_pk_bf16_f32 v51, v50, v51
	v_cvt_pk_bf16_f32 v50, v62, v52
	v_mad_i64_i32 v[52:53], s[26:27], v80, s51, v[120:121]
	v_lshl_add_u64 v[52:53], v[52:53], 0, s[24:25]
	v_lshl_add_u64 v[52:53], v[52:53], 0, s[6:7]
	v_add_u32_e32 v64, 0x90, v152
	v_lshl_add_u64 v[52:53], v[52:53], 0, v[136:137]
	v_ashrrev_i32_e32 v65, 31, v64
	global_store_dwordx4 v[52:53], v[48:51], off
	v_mov_b32_e32 v66, v44
	v_mov_b32_e32 v67, v40
	v_lshlrev_b64 v[48:49], 6, v[64:65]
	v_lshl_add_u64 v[60:61], s[74:75], 0, v[48:49]
	global_load_dwordx4 v[48:51], v[60:61], off
	global_load_dwordx4 v[52:55], v[60:61], off offset:16
	global_load_dwordx4 v[56:59], v[60:61], off offset:32
	s_nop 0
	global_load_dwordx4 v[60:63], v[60:61], off offset:48
	v_mov_b32_e32 v40, v45
	v_mov_b32_e32 v44, v46
	v_mov_b32_e32 v45, v42
	v_mov_b32_e32 v42, v47
	v_mov_b32_e32 v46, v32
	v_mov_b32_e32 v47, v36
	v_mov_b32_e32 v36, v33
	s_waitcnt vmcnt(2)
	v_pk_add_f32 v[48:49], v[48:49], v[50:51]
	v_pk_add_f32 v[52:53], v[52:53], v[54:55]
	s_waitcnt vmcnt(0)
	v_pk_add_f32 v[56:57], v[56:57], v[58:59]
	v_pk_add_f32 v[60:61], v[60:61], v[62:63]
	v_pk_add_f32 v[48:49], v[48:49], v[52:53]
	v_pk_add_f32 v[56:57], v[56:57], v[60:61]
	v_mul_f32_e32 v66, v66, v67
	v_mul_f32_e32 v40, v40, v41
	v_mul_f32_e32 v44, v44, v45
	v_mul_f32_e32 v36, v36, v37
	v_pk_add_f32 v[48:49], v[48:49], v[56:57]
	v_mul_f32_e32 v34, v34, v38
	v_mul_f32_e32 v42, v42, v43
	v_mul_f32_e32 v46, v46, v47
	v_mul_f32_e32 v35, v35, v39
	v_add_f32_e32 v48, v48, v49
	v_fmamk_f32 v48, v48, 0x3a800000, v160
	v_rsq_f32_e32 v49, v48
	s_nop 0
	v_mul_f32_e32 v49, 0xbfb8aa3b, v49
	v_mul_f32_e32 v67, v49, v67
	v_mul_f32_e32 v41, v49, v41
	v_mul_f32_e32 v45, v49, v45
	v_mul_f32_e32 v37, v49, v37
	v_mul_f32_e32 v38, v49, v38
	v_mul_f32_e32 v43, v49, v43
	v_mul_f32_e32 v47, v49, v47
	v_mul_f32_e32 v39, v49, v39
	v_exp_f32_e32 v67, v67
	v_exp_f32_e32 v41, v41
	v_exp_f32_e32 v45, v45
	v_exp_f32_e32 v37, v37
	v_exp_f32_e32 v38, v38
	v_exp_f32_e32 v43, v43
	v_exp_f32_e32 v47, v47
	v_exp_f32_e32 v39, v39
	v_fma_f32 v67, v67, v48, v48
	v_fma_f32 v41, v41, v48, v48
	v_fma_f32 v45, v45, v48, v48
	v_fma_f32 v37, v37, v48, v48
	v_fma_f32 v38, v38, v48, v48
	v_fma_f32 v43, v43, v48, v48
	v_fma_f32 v47, v47, v48, v48
	v_fma_f32 v39, v39, v48, v48
	v_rcp_f32_e32 v67, v67
	v_rcp_f32_e32 v41, v41
	v_rcp_f32_e32 v45, v45
	v_rcp_f32_e32 v37, v37
	v_rcp_f32_e32 v38, v38
	v_rcp_f32_e32 v43, v43
	v_rcp_f32_e32 v47, v47
	v_rcp_f32_e32 v39, v39
	v_mul_f32_e32 v66, v66, v67
	v_mul_f32_e32 v40, v40, v41
	v_mul_f32_e32 v44, v44, v45
	v_mul_f32_e32 v36, v36, v37
	v_mul_f32_e32 v34, v34, v38
	v_mul_f32_e32 v42, v42, v43
	v_mul_f32_e32 v46, v46, v47
	v_mul_f32_e32 v35, v35, v39
	v_cvt_pk_bf16_f32 v32, v66, v40
	v_cvt_pk_bf16_f32 v33, v44, v42
	v_cvt_pk_bf16_f32 v35, v34, v35
	v_cvt_pk_bf16_f32 v34, v46, v36
	v_mad_i64_i32 v[36:37], s[26:27], v64, s51, v[120:121]
	v_lshl_add_u64 v[36:37], v[36:37], 0, s[24:25]
	v_lshl_add_u64 v[36:37], v[36:37], 0, s[6:7]
	v_add_u32_e32 v48, 0xa0, v152
	v_lshl_add_u64 v[36:37], v[36:37], 0, v[136:137]
	v_ashrrev_i32_e32 v49, 31, v48
	global_store_dwordx4 v[36:37], v[32:35], off
	v_mov_b32_e32 v50, v28
	v_mov_b32_e32 v51, v24
	v_lshlrev_b64 v[32:33], 6, v[48:49]
	v_lshl_add_u64 v[44:45], s[74:75], 0, v[32:33]
	global_load_dwordx4 v[32:35], v[44:45], off
	global_load_dwordx4 v[36:39], v[44:45], off offset:16
	global_load_dwordx4 v[40:43], v[44:45], off offset:32
	s_nop 0
	global_load_dwordx4 v[44:47], v[44:45], off offset:48
	v_mov_b32_e32 v24, v29
	v_mov_b32_e32 v28, v30
	v_mov_b32_e32 v29, v26
	v_mov_b32_e32 v26, v31
	v_mov_b32_e32 v30, v16
	v_mov_b32_e32 v31, v20
	v_mov_b32_e32 v20, v17
	s_waitcnt vmcnt(2)
	v_pk_add_f32 v[32:33], v[32:33], v[34:35]
	v_pk_add_f32 v[36:37], v[36:37], v[38:39]
	s_waitcnt vmcnt(0)
	v_pk_add_f32 v[40:41], v[40:41], v[42:43]
	v_pk_add_f32 v[44:45], v[44:45], v[46:47]
	v_pk_add_f32 v[32:33], v[32:33], v[36:37]
	v_pk_add_f32 v[40:41], v[40:41], v[44:45]
	v_mul_f32_e32 v50, v50, v51
	v_mul_f32_e32 v24, v24, v25
	v_mul_f32_e32 v28, v28, v29
	v_mul_f32_e32 v20, v20, v21
	v_pk_add_f32 v[32:33], v[32:33], v[40:41]
	v_mul_f32_e32 v18, v18, v22
	v_mul_f32_e32 v26, v26, v27
	v_mul_f32_e32 v30, v30, v31
	v_mul_f32_e32 v19, v19, v23
	v_add_f32_e32 v32, v32, v33
	v_fmamk_f32 v32, v32, 0x3a800000, v160
	v_rsq_f32_e32 v33, v32
	s_nop 0
	v_mul_f32_e32 v33, 0xbfb8aa3b, v33
	v_mul_f32_e32 v51, v33, v51
	v_mul_f32_e32 v25, v33, v25
	v_mul_f32_e32 v29, v33, v29
	v_mul_f32_e32 v21, v33, v21
	v_mul_f32_e32 v22, v33, v22
	v_mul_f32_e32 v27, v33, v27
	v_mul_f32_e32 v31, v33, v31
	v_mul_f32_e32 v23, v33, v23
	v_exp_f32_e32 v51, v51
	v_exp_f32_e32 v25, v25
	v_exp_f32_e32 v29, v29
	v_exp_f32_e32 v21, v21
	v_exp_f32_e32 v22, v22
	v_exp_f32_e32 v27, v27
	v_exp_f32_e32 v31, v31
	v_exp_f32_e32 v23, v23
	v_fma_f32 v51, v51, v32, v32
	v_fma_f32 v25, v25, v32, v32
	v_fma_f32 v29, v29, v32, v32
	v_fma_f32 v21, v21, v32, v32
	v_fma_f32 v22, v22, v32, v32
	v_fma_f32 v27, v27, v32, v32
	v_fma_f32 v31, v31, v32, v32
	v_fma_f32 v23, v23, v32, v32
	v_rcp_f32_e32 v51, v51
	v_rcp_f32_e32 v25, v25
	v_rcp_f32_e32 v29, v29
	v_rcp_f32_e32 v21, v21
	v_rcp_f32_e32 v22, v22
	v_rcp_f32_e32 v27, v27
	v_rcp_f32_e32 v31, v31
	v_rcp_f32_e32 v23, v23
	v_mul_f32_e32 v50, v50, v51
	v_mul_f32_e32 v24, v24, v25
	v_mul_f32_e32 v28, v28, v29
	v_mul_f32_e32 v20, v20, v21
	v_mul_f32_e32 v18, v18, v22
	v_mul_f32_e32 v26, v26, v27
	v_mul_f32_e32 v30, v30, v31
	v_mul_f32_e32 v19, v19, v23
	v_cvt_pk_bf16_f32 v16, v50, v24
	v_cvt_pk_bf16_f32 v17, v28, v26
	v_cvt_pk_bf16_f32 v19, v18, v19
	v_cvt_pk_bf16_f32 v18, v30, v20
	v_mad_i64_i32 v[20:21], s[26:27], v48, s51, v[120:121]
	v_lshl_add_u64 v[20:21], v[20:21], 0, s[24:25]
	v_lshl_add_u64 v[20:21], v[20:21], 0, s[6:7]
	v_add_u32_e32 v32, 0xb0, v152
	v_lshl_add_u64 v[20:21], v[20:21], 0, v[136:137]
	v_ashrrev_i32_e32 v33, 31, v32
	global_store_dwordx4 v[20:21], v[16:19], off
	v_mov_b32_e32 v34, v12
	v_mov_b32_e32 v35, v8
	v_lshlrev_b64 v[16:17], 6, v[32:33]
	v_lshl_add_u64 v[28:29], s[74:75], 0, v[16:17]
	global_load_dwordx4 v[16:19], v[28:29], off
	global_load_dwordx4 v[20:23], v[28:29], off offset:16
	global_load_dwordx4 v[24:27], v[28:29], off offset:32
	s_nop 0
	global_load_dwordx4 v[28:31], v[28:29], off offset:48
	v_mov_b32_e32 v8, v13
	v_mov_b32_e32 v12, v14
	v_mov_b32_e32 v13, v10
	v_mov_b32_e32 v10, v15
	v_mov_b32_e32 v14, v0
	v_mov_b32_e32 v15, v4
	v_mov_b32_e32 v4, v1
	s_waitcnt vmcnt(2)
	v_pk_add_f32 v[16:17], v[16:17], v[18:19]
	v_pk_add_f32 v[20:21], v[20:21], v[22:23]
	s_waitcnt vmcnt(0)
	v_pk_add_f32 v[24:25], v[24:25], v[26:27]
	v_pk_add_f32 v[28:29], v[28:29], v[30:31]
	v_pk_add_f32 v[16:17], v[16:17], v[20:21]
	v_pk_add_f32 v[24:25], v[24:25], v[28:29]
	v_mul_f32_e32 v34, v34, v35
	v_mul_f32_e32 v8, v8, v9
	v_mul_f32_e32 v12, v12, v13
	v_mul_f32_e32 v4, v4, v5
	v_pk_add_f32 v[16:17], v[16:17], v[24:25]
	v_mul_f32_e32 v2, v2, v6
	v_mul_f32_e32 v10, v10, v11
	v_mul_f32_e32 v14, v14, v15
	v_mul_f32_e32 v3, v3, v7
	v_add_f32_e32 v16, v16, v17
	v_fmamk_f32 v16, v16, 0x3a800000, v160
	v_rsq_f32_e32 v17, v16
	s_nop 0
	v_mul_f32_e32 v17, 0xbfb8aa3b, v17
	v_mul_f32_e32 v35, v17, v35
	v_mul_f32_e32 v9, v17, v9
	v_mul_f32_e32 v13, v17, v13
	v_mul_f32_e32 v5, v17, v5
	v_mul_f32_e32 v6, v17, v6
	v_mul_f32_e32 v11, v17, v11
	v_mul_f32_e32 v15, v17, v15
	v_mul_f32_e32 v7, v17, v7
	v_exp_f32_e32 v35, v35
	v_exp_f32_e32 v9, v9
	v_exp_f32_e32 v13, v13
	v_exp_f32_e32 v5, v5
	v_exp_f32_e32 v6, v6
	v_exp_f32_e32 v11, v11
	v_exp_f32_e32 v15, v15
	v_exp_f32_e32 v7, v7
	v_fma_f32 v35, v35, v16, v16
	v_fma_f32 v9, v9, v16, v16
	v_fma_f32 v13, v13, v16, v16
	v_fma_f32 v5, v5, v16, v16
	v_fma_f32 v6, v6, v16, v16
	v_fma_f32 v11, v11, v16, v16
	v_fma_f32 v15, v15, v16, v16
	v_fma_f32 v7, v7, v16, v16
	v_rcp_f32_e32 v35, v35
	v_rcp_f32_e32 v9, v9
	v_rcp_f32_e32 v13, v13
	v_rcp_f32_e32 v5, v5
	v_rcp_f32_e32 v6, v6
	v_rcp_f32_e32 v11, v11
	v_rcp_f32_e32 v15, v15
	v_rcp_f32_e32 v7, v7
	v_mul_f32_e32 v34, v34, v35
	v_mul_f32_e32 v8, v8, v9
	v_mul_f32_e32 v12, v12, v13
	v_mul_f32_e32 v4, v4, v5
	v_mul_f32_e32 v2, v2, v6
	v_mul_f32_e32 v10, v10, v11
	v_mul_f32_e32 v14, v14, v15
	v_mul_f32_e32 v3, v3, v7
	v_cvt_pk_bf16_f32 v0, v34, v8
	v_cvt_pk_bf16_f32 v1, v12, v10
	v_cvt_pk_bf16_f32 v3, v2, v3
	v_cvt_pk_bf16_f32 v2, v14, v4
	v_mad_i64_i32 v[4:5], s[26:27], v32, s51, v[120:121]
	v_lshl_add_u64 v[4:5], v[4:5], 0, s[24:25]
	v_lshl_add_u64 v[4:5], v[4:5], 0, s[6:7]
	v_lshl_add_u64 v[4:5], v[4:5], 0, v[136:137]
	global_store_dwordx4 v[4:5], v[0:3], off
	s_andn2_b64 vcc, exec, s[4:5]
	s_mov_b64 s[4:5], -1
	s_cbranch_vccnz .LBB0_157
	s_branch .LBB0_191

.LBB0_981:
	v_ashrrev_i32_e32 v153, 31, v152
	v_lshlrev_b64 v[154:155], 6, v[152:153]
	v_lshl_add_u64 v[170:171], s[74:75], 0, v[154:155]
	s_waitcnt lgkmcnt(0)
	global_load_dwordx4 v[154:157], v[170:171], off
	global_load_dwordx4 v[162:165], v[170:171], off offset:16
	global_load_dwordx4 v[166:169], v[170:171], off offset:32
	s_nop 0
	global_load_dwordx4 v[170:173], v[170:171], off offset:48
	v_mov_b32_e32 v174, v124
	v_mov_b32_e32 v175, v116
	v_mov_b32_e32 v116, v125
	v_mov_b32_e32 v124, v126
	v_mov_b32_e32 v125, v118
	v_mov_b32_e32 v118, v127
	v_mov_b32_e32 v126, v120
	v_mov_b32_e32 v127, v112
	v_mov_b32_e32 v112, v121
	v_mov_b32_e32 v176, v122
	v_mov_b32_e32 v177, v114
	v_mov_b32_e32 v114, v123
	s_lshl_b32 s26, s26, 7
	v_mov_b64_e32 v[120:121], s[72:73]
	s_ashr_i32 s27, s26, 31
	v_mad_i64_i32 v[122:123], s[28:29], v152, s53, v[120:121]
	s_lshl_b64 s[26:27], s[26:27], 1
	v_lshl_add_u64 v[122:123], v[122:123], 0, s[26:27]
	v_lshl_add_u64 v[122:123], v[122:123], 0, s[8:9]
	s_waitcnt vmcnt(2)
	v_pk_add_f32 v[154:155], v[154:155], v[156:157]
	v_pk_add_f32 v[162:163], v[162:163], v[164:165]
	s_waitcnt vmcnt(0)
	v_pk_add_f32 v[166:167], v[166:167], v[168:169]
	v_pk_add_f32 v[170:171], v[170:171], v[172:173]
	v_pk_add_f32 v[154:155], v[154:155], v[162:163]
	v_pk_add_f32 v[166:167], v[166:167], v[170:171]
	v_mul_f32_e32 v116, v116, v117
	v_mul_f32_e32 v124, v124, v125
	v_mul_f32_e32 v118, v118, v119
	v_mul_f32_e32 v126, v126, v127
	v_pk_add_f32 v[154:155], v[154:155], v[166:167]
	v_mul_f32_e32 v174, v174, v175
	v_mul_f32_e32 v112, v112, v113
	v_mul_f32_e32 v176, v176, v177
	v_mul_f32_e32 v114, v114, v115
	v_add_f32_e32 v154, v154, v155
	v_fmamk_f32 v154, v154, 0x3a800000, v160
	v_rsq_f32_e32 v155, v154
	s_nop 0
	v_mul_f32_e32 v155, 0xbfb8aa3b, v155
	v_mul_f32_e32 v117, v155, v117
	v_mul_f32_e32 v125, v155, v125
	v_mul_f32_e32 v119, v155, v119
	v_mul_f32_e32 v127, v155, v127
	v_mul_f32_e32 v175, v155, v175
	v_mul_f32_e32 v113, v155, v113
	v_mul_f32_e32 v177, v155, v177
	v_mul_f32_e32 v115, v155, v115
	v_exp_f32_e32 v117, v117
	v_exp_f32_e32 v125, v125
	v_exp_f32_e32 v119, v119
	v_exp_f32_e32 v127, v127
	v_exp_f32_e32 v175, v175
	v_exp_f32_e32 v113, v113
	v_exp_f32_e32 v177, v177
	v_exp_f32_e32 v115, v115
	v_fma_f32 v117, v117, v154, v154
	v_fma_f32 v125, v125, v154, v154
	v_fma_f32 v119, v119, v154, v154
	v_fma_f32 v127, v127, v154, v154
	v_fma_f32 v175, v175, v154, v154
	v_fma_f32 v113, v113, v154, v154
	v_fma_f32 v177, v177, v154, v154
	v_fma_f32 v115, v115, v154, v154
	v_rcp_f32_e32 v117, v117
	v_rcp_f32_e32 v125, v125
	v_rcp_f32_e32 v119, v119
	v_rcp_f32_e32 v127, v127
	v_rcp_f32_e32 v175, v175
	v_rcp_f32_e32 v113, v113
	v_rcp_f32_e32 v177, v177
	v_rcp_f32_e32 v115, v115
	v_mul_f32_e32 v116, v116, v117
	v_mul_f32_e32 v124, v124, v125
	v_mul_f32_e32 v118, v118, v119
	v_mul_f32_e32 v126, v126, v127
	v_mul_f32_e32 v174, v174, v175
	v_mul_f32_e32 v112, v112, v113
	v_mul_f32_e32 v176, v176, v177
	v_mul_f32_e32 v114, v114, v115
	v_cvt_pk_bf16_f32 v113, v124, v118
	v_cvt_pk_bf16_f32 v115, v176, v114
	v_cvt_pk_bf16_f32 v114, v126, v112
	v_cvt_pk_bf16_f32 v112, v174, v116
	v_or_b32_e32 v126, 16, v152
	v_lshl_add_u64 v[116:117], v[122:123], 0, v[136:137]
	v_ashrrev_i32_e32 v127, 31, v126
	global_store_dwordx4 v[116:117], v[112:115], off
	v_mov_b32_e32 v162, v108
	v_mov_b32_e32 v163, v100
	v_lshlrev_b64 v[112:113], 6, v[126:127]
	v_lshl_add_u64 v[154:155], s[74:75], 0, v[112:113]
	global_load_dwordx4 v[112:115], v[154:155], off
	global_load_dwordx4 v[116:119], v[154:155], off offset:16
	global_load_dwordx4 v[122:125], v[154:155], off offset:32
	s_nop 0
	global_load_dwordx4 v[154:157], v[154:155], off offset:48
	v_mov_b32_e32 v100, v109
	v_mov_b32_e32 v108, v110
	v_mov_b32_e32 v109, v102
	v_mov_b32_e32 v102, v111
	v_mov_b32_e32 v110, v104
	v_mov_b32_e32 v111, v96
	v_mov_b32_e32 v96, v105
	v_mov_b32_e32 v104, v106
	v_mov_b32_e32 v105, v98
	v_mov_b32_e32 v98, v107
	s_waitcnt vmcnt(2)
	v_pk_add_f32 v[112:113], v[112:113], v[114:115]
	v_pk_add_f32 v[116:117], v[116:117], v[118:119]
	s_waitcnt vmcnt(0)
	v_pk_add_f32 v[122:123], v[122:123], v[124:125]
	v_pk_add_f32 v[154:155], v[154:155], v[156:157]
	v_pk_add_f32 v[112:113], v[112:113], v[116:117]
	v_pk_add_f32 v[122:123], v[122:123], v[154:155]
	v_mul_f32_e32 v100, v100, v101
	v_mul_f32_e32 v108, v108, v109
	v_mul_f32_e32 v162, v162, v163
	v_mul_f32_e32 v102, v102, v103
	v_pk_add_f32 v[112:113], v[112:113], v[122:123]
	v_mul_f32_e32 v110, v110, v111
	v_mul_f32_e32 v96, v96, v97
	v_mul_f32_e32 v104, v104, v105
	v_mul_f32_e32 v98, v98, v99
	v_add_f32_e32 v112, v112, v113
	v_fmamk_f32 v112, v112, 0x3a800000, v160
	v_rsq_f32_e32 v113, v112
	s_nop 0
	v_mul_f32_e32 v113, 0xbfb8aa3b, v113
	v_mul_f32_e32 v101, v113, v101
	v_mul_f32_e32 v109, v113, v109
	v_mul_f32_e32 v163, v113, v163
	v_mul_f32_e32 v103, v113, v103
	v_mul_f32_e32 v111, v113, v111
	v_mul_f32_e32 v97, v113, v97
	v_mul_f32_e32 v105, v113, v105
	v_mul_f32_e32 v99, v113, v99
	v_exp_f32_e32 v101, v101
	v_exp_f32_e32 v109, v109
	v_exp_f32_e32 v163, v163
	v_exp_f32_e32 v103, v103
	v_exp_f32_e32 v111, v111
	v_exp_f32_e32 v97, v97
	v_exp_f32_e32 v105, v105
	v_exp_f32_e32 v99, v99
	v_fma_f32 v101, v101, v112, v112
	v_fma_f32 v109, v109, v112, v112
	v_fma_f32 v163, v163, v112, v112
	v_fma_f32 v103, v103, v112, v112
	v_fma_f32 v111, v111, v112, v112
	v_fma_f32 v97, v97, v112, v112
	v_fma_f32 v105, v105, v112, v112
	v_fma_f32 v99, v99, v112, v112
	v_rcp_f32_e32 v101, v101
	v_rcp_f32_e32 v109, v109
	v_rcp_f32_e32 v163, v163
	v_rcp_f32_e32 v103, v103
	v_rcp_f32_e32 v111, v111
	v_rcp_f32_e32 v97, v97
	v_rcp_f32_e32 v105, v105
	v_rcp_f32_e32 v99, v99
	v_mul_f32_e32 v100, v100, v101
	v_mul_f32_e32 v108, v108, v109
	v_mul_f32_e32 v162, v162, v163
	v_mul_f32_e32 v102, v102, v103
	v_mul_f32_e32 v110, v110, v111
	v_mul_f32_e32 v96, v96, v97
	v_mul_f32_e32 v104, v104, v105
	v_mul_f32_e32 v98, v98, v99
	v_cvt_pk_bf16_f32 v97, v108, v102
	v_cvt_pk_bf16_f32 v99, v104, v98
	v_cvt_pk_bf16_f32 v98, v110, v96
	v_cvt_pk_bf16_f32 v96, v162, v100
	v_mad_i64_i32 v[112:113], s[28:29], v126, s53, v[120:121]
	v_lshl_add_u64 v[112:113], v[112:113], 0, s[26:27]
	v_lshl_add_u64 v[100:101], v[112:113], 0, s[8:9]
	v_or_b32_e32 v112, 32, v152
	v_lshl_add_u64 v[100:101], v[100:101], 0, v[136:137]
	v_ashrrev_i32_e32 v113, 31, v112
	global_store_dwordx4 v[100:101], v[96:99], off
	v_mov_b32_e32 v114, v92
	v_mov_b32_e32 v92, v94
	v_lshlrev_b64 v[96:97], 6, v[112:113]
	v_lshl_add_u64 v[108:109], s[74:75], 0, v[96:97]
	global_load_dwordx4 v[96:99], v[108:109], off
	global_load_dwordx4 v[100:103], v[108:109], off offset:16
	global_load_dwordx4 v[104:107], v[108:109], off offset:32
	s_nop 0
	global_load_dwordx4 v[108:111], v[108:109], off offset:48
	v_mov_b32_e32 v94, v80
	v_mov_b32_e32 v80, v82
	v_mov_b32_e32 v115, v88
	v_mov_b32_e32 v88, v93
	v_mov_b32_e32 v93, v90
	v_mov_b32_e32 v90, v95
	v_mov_b32_e32 v95, v84
	v_mov_b32_e32 v84, v81
	v_mov_b32_e32 v81, v86
	v_mov_b32_e32 v86, v83
	s_waitcnt vmcnt(2)
	v_pk_add_f32 v[96:97], v[96:97], v[98:99]
	v_pk_add_f32 v[100:101], v[100:101], v[102:103]
	s_waitcnt vmcnt(0)
	v_pk_add_f32 v[104:105], v[104:105], v[106:107]
	v_pk_add_f32 v[108:109], v[108:109], v[110:111]
	v_pk_add_f32 v[96:97], v[96:97], v[100:101]
	v_pk_add_f32 v[104:105], v[104:105], v[108:109]
	v_mul_f32_e32 v114, v114, v115
	v_mul_f32_e32 v88, v88, v89
	v_mul_f32_e32 v92, v92, v93
	v_mul_f32_e32 v90, v90, v91
	v_pk_add_f32 v[96:97], v[96:97], v[104:105]
	v_mul_f32_e32 v94, v94, v95
	v_mul_f32_e32 v84, v84, v85
	v_mul_f32_e32 v80, v80, v81
	v_mul_f32_e32 v86, v86, v87
	v_add_f32_e32 v96, v96, v97
	v_fmamk_f32 v96, v96, 0x3a800000, v160
	v_rsq_f32_e32 v97, v96
	s_nop 0
	v_mul_f32_e32 v97, 0xbfb8aa3b, v97
	v_mul_f32_e32 v115, v97, v115
	v_mul_f32_e32 v89, v97, v89
	v_mul_f32_e32 v93, v97, v93
	v_mul_f32_e32 v91, v97, v91
	v_mul_f32_e32 v95, v97, v95
	v_mul_f32_e32 v85, v97, v85
	v_mul_f32_e32 v81, v97, v81
	v_mul_f32_e32 v87, v97, v87
	v_exp_f32_e32 v115, v115
	v_exp_f32_e32 v89, v89
	v_exp_f32_e32 v93, v93
	v_exp_f32_e32 v91, v91
	v_exp_f32_e32 v95, v95
	v_exp_f32_e32 v85, v85
	v_exp_f32_e32 v81, v81
	v_exp_f32_e32 v87, v87
	v_fma_f32 v115, v115, v96, v96
	v_fma_f32 v89, v89, v96, v96
	v_fma_f32 v93, v93, v96, v96
	v_fma_f32 v91, v91, v96, v96
	v_fma_f32 v95, v95, v96, v96
	v_fma_f32 v85, v85, v96, v96
	v_fma_f32 v81, v81, v96, v96
	v_fma_f32 v87, v87, v96, v96
	v_rcp_f32_e32 v115, v115
	v_rcp_f32_e32 v89, v89
	v_rcp_f32_e32 v93, v93
	v_rcp_f32_e32 v91, v91
	v_rcp_f32_e32 v95, v95
	v_rcp_f32_e32 v85, v85
	v_rcp_f32_e32 v81, v81
	v_rcp_f32_e32 v87, v87
	v_mul_f32_e32 v114, v114, v115
	v_mul_f32_e32 v88, v88, v89
	v_mul_f32_e32 v92, v92, v93
	v_mul_f32_e32 v90, v90, v91
	v_mul_f32_e32 v94, v94, v95
	v_mul_f32_e32 v84, v84, v85
	v_mul_f32_e32 v80, v80, v81
	v_mul_f32_e32 v86, v86, v87
	v_cvt_pk_bf16_f32 v81, v92, v90
	v_cvt_pk_bf16_f32 v82, v94, v84
	v_cvt_pk_bf16_f32 v83, v80, v86
	v_cvt_pk_bf16_f32 v80, v114, v88
	v_mad_i64_i32 v[96:97], s[28:29], v112, s53, v[120:121]
	v_lshl_add_u64 v[84:85], v[96:97], 0, s[26:27]
	v_lshl_add_u64 v[84:85], v[84:85], 0, s[8:9]
	v_or_b32_e32 v96, 48, v152
	v_lshl_add_u64 v[84:85], v[84:85], 0, v[136:137]
	v_ashrrev_i32_e32 v97, 31, v96
	global_store_dwordx4 v[84:85], v[80:83], off
	v_mov_b32_e32 v98, v76
	v_mov_b32_e32 v99, v72
	v_lshlrev_b64 v[80:81], 6, v[96:97]
	v_lshl_add_u64 v[92:93], s[74:75], 0, v[80:81]
	global_load_dwordx4 v[80:83], v[92:93], off
	global_load_dwordx4 v[84:87], v[92:93], off offset:16
	global_load_dwordx4 v[88:91], v[92:93], off offset:32
	s_nop 0
	global_load_dwordx4 v[92:95], v[92:93], off offset:48
	v_mov_b32_e32 v72, v77
	v_mov_b32_e32 v76, v78
	v_mov_b32_e32 v77, v74
	v_mov_b32_e32 v74, v79
	v_mov_b32_e32 v78, v64
	v_mov_b32_e32 v79, v68
	v_mov_b32_e32 v68, v65
	s_waitcnt vmcnt(2)
	v_pk_add_f32 v[80:81], v[80:81], v[82:83]
	v_pk_add_f32 v[84:85], v[84:85], v[86:87]
	s_waitcnt vmcnt(0)
	v_pk_add_f32 v[88:89], v[88:89], v[90:91]
	v_pk_add_f32 v[92:93], v[92:93], v[94:95]
	v_pk_add_f32 v[80:81], v[80:81], v[84:85]
	v_pk_add_f32 v[88:89], v[88:89], v[92:93]
	v_mul_f32_e32 v98, v98, v99
	v_mul_f32_e32 v72, v72, v73
	v_mul_f32_e32 v76, v76, v77
	v_mul_f32_e32 v68, v68, v69
	v_pk_add_f32 v[80:81], v[80:81], v[88:89]
	v_mul_f32_e32 v66, v66, v70
	v_mul_f32_e32 v74, v74, v75
	v_mul_f32_e32 v78, v78, v79
	v_mul_f32_e32 v67, v67, v71
	v_add_f32_e32 v80, v80, v81
	v_fmamk_f32 v80, v80, 0x3a800000, v160
	v_rsq_f32_e32 v81, v80
	s_nop 0
	v_mul_f32_e32 v81, 0xbfb8aa3b, v81
	v_mul_f32_e32 v99, v81, v99
	v_mul_f32_e32 v73, v81, v73
	v_mul_f32_e32 v77, v81, v77
	v_mul_f32_e32 v69, v81, v69
	v_mul_f32_e32 v70, v81, v70
	v_mul_f32_e32 v75, v81, v75
	v_mul_f32_e32 v79, v81, v79
	v_mul_f32_e32 v71, v81, v71
	v_exp_f32_e32 v99, v99
	v_exp_f32_e32 v73, v73
	v_exp_f32_e32 v77, v77
	v_exp_f32_e32 v69, v69
	v_exp_f32_e32 v70, v70
	v_exp_f32_e32 v75, v75
	v_exp_f32_e32 v79, v79
	v_exp_f32_e32 v71, v71
	v_fma_f32 v99, v99, v80, v80
	v_fma_f32 v73, v73, v80, v80
	v_fma_f32 v77, v77, v80, v80
	v_fma_f32 v69, v69, v80, v80
	v_fma_f32 v70, v70, v80, v80
	v_fma_f32 v75, v75, v80, v80
	v_fma_f32 v79, v79, v80, v80
	v_fma_f32 v71, v71, v80, v80
	v_rcp_f32_e32 v99, v99
	v_rcp_f32_e32 v73, v73
	v_rcp_f32_e32 v77, v77
	v_rcp_f32_e32 v69, v69
	v_rcp_f32_e32 v70, v70
	v_rcp_f32_e32 v75, v75
	v_rcp_f32_e32 v79, v79
	v_rcp_f32_e32 v71, v71
	v_mul_f32_e32 v98, v98, v99
	v_mul_f32_e32 v72, v72, v73
	v_mul_f32_e32 v76, v76, v77
	v_mul_f32_e32 v68, v68, v69
	v_mul_f32_e32 v66, v66, v70
	v_mul_f32_e32 v74, v74, v75
	v_mul_f32_e32 v78, v78, v79
	v_mul_f32_e32 v67, v67, v71
	v_cvt_pk_bf16_f32 v64, v98, v72
	v_cvt_pk_bf16_f32 v65, v76, v74
	v_cvt_pk_bf16_f32 v67, v66, v67
	v_cvt_pk_bf16_f32 v66, v78, v68
	v_mad_i64_i32 v[68:69], s[28:29], v96, s53, v[120:121]
	v_lshl_add_u64 v[68:69], v[68:69], 0, s[26:27]
	v_lshl_add_u64 v[68:69], v[68:69], 0, s[8:9]
	v_add_u32_e32 v80, 0x80, v152
	v_lshl_add_u64 v[68:69], v[68:69], 0, v[136:137]
	v_ashrrev_i32_e32 v81, 31, v80
	global_store_dwordx4 v[68:69], v[64:67], off
	v_mov_b32_e32 v82, v60
	v_mov_b32_e32 v83, v56
	v_lshlrev_b64 v[64:65], 6, v[80:81]
	v_lshl_add_u64 v[76:77], s[74:75], 0, v[64:65]
	global_load_dwordx4 v[64:67], v[76:77], off
	global_load_dwordx4 v[68:71], v[76:77], off offset:16
	global_load_dwordx4 v[72:75], v[76:77], off offset:32
	s_nop 0
	global_load_dwordx4 v[76:79], v[76:77], off offset:48
	v_mov_b32_e32 v56, v61
	v_mov_b32_e32 v60, v62
	v_mov_b32_e32 v61, v58
	v_mov_b32_e32 v58, v63
	v_mov_b32_e32 v62, v48
	v_mov_b32_e32 v63, v52
	v_mov_b32_e32 v52, v49
	s_waitcnt vmcnt(2)
	v_pk_add_f32 v[64:65], v[64:65], v[66:67]
	v_pk_add_f32 v[68:69], v[68:69], v[70:71]
	s_waitcnt vmcnt(0)
	v_pk_add_f32 v[72:73], v[72:73], v[74:75]
	v_pk_add_f32 v[76:77], v[76:77], v[78:79]
	v_pk_add_f32 v[64:65], v[64:65], v[68:69]
	v_pk_add_f32 v[72:73], v[72:73], v[76:77]
	v_mul_f32_e32 v82, v82, v83
	v_mul_f32_e32 v56, v56, v57
	v_mul_f32_e32 v60, v60, v61
	v_mul_f32_e32 v52, v52, v53
	v_pk_add_f32 v[64:65], v[64:65], v[72:73]
	v_mul_f32_e32 v50, v50, v54
	v_mul_f32_e32 v58, v58, v59
	v_mul_f32_e32 v62, v62, v63
	v_mul_f32_e32 v51, v51, v55
	v_add_f32_e32 v64, v64, v65
	v_fmamk_f32 v64, v64, 0x3a800000, v160
	v_rsq_f32_e32 v65, v64
	s_nop 0
	v_mul_f32_e32 v65, 0xbfb8aa3b, v65
	v_mul_f32_e32 v83, v65, v83
	v_mul_f32_e32 v57, v65, v57
	v_mul_f32_e32 v61, v65, v61
	v_mul_f32_e32 v53, v65, v53
	v_mul_f32_e32 v54, v65, v54
	v_mul_f32_e32 v59, v65, v59
	v_mul_f32_e32 v63, v65, v63
	v_mul_f32_e32 v55, v65, v55
	v_exp_f32_e32 v83, v83
	v_exp_f32_e32 v57, v57
	v_exp_f32_e32 v61, v61
	v_exp_f32_e32 v53, v53
	v_exp_f32_e32 v54, v54
	v_exp_f32_e32 v59, v59
	v_exp_f32_e32 v63, v63
	v_exp_f32_e32 v55, v55
	v_fma_f32 v83, v83, v64, v64
	v_fma_f32 v57, v57, v64, v64
	v_fma_f32 v61, v61, v64, v64
	v_fma_f32 v53, v53, v64, v64
	v_fma_f32 v54, v54, v64, v64
	v_fma_f32 v59, v59, v64, v64
	v_fma_f32 v63, v63, v64, v64
	v_fma_f32 v55, v55, v64, v64
	v_rcp_f32_e32 v83, v83
	v_rcp_f32_e32 v57, v57
	v_rcp_f32_e32 v61, v61
	v_rcp_f32_e32 v53, v53
	v_rcp_f32_e32 v54, v54
	v_rcp_f32_e32 v59, v59
	v_rcp_f32_e32 v63, v63
	v_rcp_f32_e32 v55, v55
	v_mul_f32_e32 v82, v82, v83
	v_mul_f32_e32 v56, v56, v57
	v_mul_f32_e32 v60, v60, v61
	v_mul_f32_e32 v52, v52, v53
	v_mul_f32_e32 v50, v50, v54
	v_mul_f32_e32 v58, v58, v59
	v_mul_f32_e32 v62, v62, v63
	v_mul_f32_e32 v51, v51, v55
	v_cvt_pk_bf16_f32 v48, v82, v56
	v_cvt_pk_bf16_f32 v49, v60, v58
	v_cvt_pk_bf16_f32 v51, v50, v51
	v_cvt_pk_bf16_f32 v50, v62, v52
	v_mad_i64_i32 v[52:53], s[28:29], v80, s53, v[120:121]
	v_lshl_add_u64 v[52:53], v[52:53], 0, s[26:27]
	v_lshl_add_u64 v[52:53], v[52:53], 0, s[8:9]
	v_add_u32_e32 v64, 0x90, v152
	v_lshl_add_u64 v[52:53], v[52:53], 0, v[136:137]
	v_ashrrev_i32_e32 v65, 31, v64
	global_store_dwordx4 v[52:53], v[48:51], off
	v_mov_b32_e32 v66, v44
	v_mov_b32_e32 v67, v40
	v_lshlrev_b64 v[48:49], 6, v[64:65]
	v_lshl_add_u64 v[60:61], s[74:75], 0, v[48:49]
	global_load_dwordx4 v[48:51], v[60:61], off
	global_load_dwordx4 v[52:55], v[60:61], off offset:16
	global_load_dwordx4 v[56:59], v[60:61], off offset:32
	s_nop 0
	global_load_dwordx4 v[60:63], v[60:61], off offset:48
	v_mov_b32_e32 v40, v45
	v_mov_b32_e32 v44, v46
	v_mov_b32_e32 v45, v42
	v_mov_b32_e32 v42, v47
	v_mov_b32_e32 v46, v32
	v_mov_b32_e32 v47, v36
	v_mov_b32_e32 v36, v33
	s_waitcnt vmcnt(2)
	v_pk_add_f32 v[48:49], v[48:49], v[50:51]
	v_pk_add_f32 v[52:53], v[52:53], v[54:55]
	s_waitcnt vmcnt(0)
	v_pk_add_f32 v[56:57], v[56:57], v[58:59]
	v_pk_add_f32 v[60:61], v[60:61], v[62:63]
	v_pk_add_f32 v[48:49], v[48:49], v[52:53]
	v_pk_add_f32 v[56:57], v[56:57], v[60:61]
	v_mul_f32_e32 v66, v66, v67
	v_mul_f32_e32 v40, v40, v41
	v_mul_f32_e32 v44, v44, v45
	v_mul_f32_e32 v36, v36, v37
	v_pk_add_f32 v[48:49], v[48:49], v[56:57]
	v_mul_f32_e32 v34, v34, v38
	v_mul_f32_e32 v42, v42, v43
	v_mul_f32_e32 v46, v46, v47
	v_mul_f32_e32 v35, v35, v39
	v_add_f32_e32 v48, v48, v49
	v_fmamk_f32 v48, v48, 0x3a800000, v160
	v_rsq_f32_e32 v49, v48
	s_nop 0
	v_mul_f32_e32 v49, 0xbfb8aa3b, v49
	v_mul_f32_e32 v67, v49, v67
	v_mul_f32_e32 v41, v49, v41
	v_mul_f32_e32 v45, v49, v45
	v_mul_f32_e32 v37, v49, v37
	v_mul_f32_e32 v38, v49, v38
	v_mul_f32_e32 v43, v49, v43
	v_mul_f32_e32 v47, v49, v47
	v_mul_f32_e32 v39, v49, v39
	v_exp_f32_e32 v67, v67
	v_exp_f32_e32 v41, v41
	v_exp_f32_e32 v45, v45
	v_exp_f32_e32 v37, v37
	v_exp_f32_e32 v38, v38
	v_exp_f32_e32 v43, v43
	v_exp_f32_e32 v47, v47
	v_exp_f32_e32 v39, v39
	v_fma_f32 v67, v67, v48, v48
	v_fma_f32 v41, v41, v48, v48
	v_fma_f32 v45, v45, v48, v48
	v_fma_f32 v37, v37, v48, v48
	v_fma_f32 v38, v38, v48, v48
	v_fma_f32 v43, v43, v48, v48
	v_fma_f32 v47, v47, v48, v48
	v_fma_f32 v39, v39, v48, v48
	v_rcp_f32_e32 v67, v67
	v_rcp_f32_e32 v41, v41
	v_rcp_f32_e32 v45, v45
	v_rcp_f32_e32 v37, v37
	v_rcp_f32_e32 v38, v38
	v_rcp_f32_e32 v43, v43
	v_rcp_f32_e32 v47, v47
	v_rcp_f32_e32 v39, v39
	v_mul_f32_e32 v66, v66, v67
	v_mul_f32_e32 v40, v40, v41
	v_mul_f32_e32 v44, v44, v45
	v_mul_f32_e32 v36, v36, v37
	v_mul_f32_e32 v34, v34, v38
	v_mul_f32_e32 v42, v42, v43
	v_mul_f32_e32 v46, v46, v47
	v_mul_f32_e32 v35, v35, v39
	v_cvt_pk_bf16_f32 v32, v66, v40
	v_cvt_pk_bf16_f32 v33, v44, v42
	v_cvt_pk_bf16_f32 v35, v34, v35
	v_cvt_pk_bf16_f32 v34, v46, v36
	v_mad_i64_i32 v[36:37], s[28:29], v64, s53, v[120:121]
	v_lshl_add_u64 v[36:37], v[36:37], 0, s[26:27]
	v_lshl_add_u64 v[36:37], v[36:37], 0, s[8:9]
	v_add_u32_e32 v48, 0xa0, v152
	v_lshl_add_u64 v[36:37], v[36:37], 0, v[136:137]
	v_ashrrev_i32_e32 v49, 31, v48
	global_store_dwordx4 v[36:37], v[32:35], off
	v_mov_b32_e32 v50, v28
	v_mov_b32_e32 v51, v24
	v_lshlrev_b64 v[32:33], 6, v[48:49]
	v_lshl_add_u64 v[44:45], s[74:75], 0, v[32:33]
	global_load_dwordx4 v[32:35], v[44:45], off
	global_load_dwordx4 v[36:39], v[44:45], off offset:16
	global_load_dwordx4 v[40:43], v[44:45], off offset:32
	s_nop 0
	global_load_dwordx4 v[44:47], v[44:45], off offset:48
	v_mov_b32_e32 v24, v29
	v_mov_b32_e32 v28, v30
	v_mov_b32_e32 v29, v26
	v_mov_b32_e32 v26, v31
	v_mov_b32_e32 v30, v16
	v_mov_b32_e32 v31, v20
	v_mov_b32_e32 v20, v17
	s_waitcnt vmcnt(2)
	v_pk_add_f32 v[32:33], v[32:33], v[34:35]
	v_pk_add_f32 v[36:37], v[36:37], v[38:39]
	s_waitcnt vmcnt(0)
	v_pk_add_f32 v[40:41], v[40:41], v[42:43]
	v_pk_add_f32 v[44:45], v[44:45], v[46:47]
	v_pk_add_f32 v[32:33], v[32:33], v[36:37]
	v_pk_add_f32 v[40:41], v[40:41], v[44:45]
	v_mul_f32_e32 v50, v50, v51
	v_mul_f32_e32 v24, v24, v25
	v_mul_f32_e32 v28, v28, v29
	v_mul_f32_e32 v20, v20, v21
	v_pk_add_f32 v[32:33], v[32:33], v[40:41]
	v_mul_f32_e32 v18, v18, v22
	v_mul_f32_e32 v26, v26, v27
	v_mul_f32_e32 v30, v30, v31
	v_mul_f32_e32 v19, v19, v23
	v_add_f32_e32 v32, v32, v33
	v_fmamk_f32 v32, v32, 0x3a800000, v160
	v_rsq_f32_e32 v33, v32
	s_nop 0
	v_mul_f32_e32 v33, 0xbfb8aa3b, v33
	v_mul_f32_e32 v51, v33, v51
	v_mul_f32_e32 v25, v33, v25
	v_mul_f32_e32 v29, v33, v29
	v_mul_f32_e32 v21, v33, v21
	v_mul_f32_e32 v22, v33, v22
	v_mul_f32_e32 v27, v33, v27
	v_mul_f32_e32 v31, v33, v31
	v_mul_f32_e32 v23, v33, v23
	v_exp_f32_e32 v51, v51
	v_exp_f32_e32 v25, v25
	v_exp_f32_e32 v29, v29
	v_exp_f32_e32 v21, v21
	v_exp_f32_e32 v22, v22
	v_exp_f32_e32 v27, v27
	v_exp_f32_e32 v31, v31
	v_exp_f32_e32 v23, v23
	v_fma_f32 v51, v51, v32, v32
	v_fma_f32 v25, v25, v32, v32
	v_fma_f32 v29, v29, v32, v32
	v_fma_f32 v21, v21, v32, v32
	v_fma_f32 v22, v22, v32, v32
	v_fma_f32 v27, v27, v32, v32
	v_fma_f32 v31, v31, v32, v32
	v_fma_f32 v23, v23, v32, v32
	v_rcp_f32_e32 v51, v51
	v_rcp_f32_e32 v25, v25
	v_rcp_f32_e32 v29, v29
	v_rcp_f32_e32 v21, v21
	v_rcp_f32_e32 v22, v22
	v_rcp_f32_e32 v27, v27
	v_rcp_f32_e32 v31, v31
	v_rcp_f32_e32 v23, v23
	v_mul_f32_e32 v50, v50, v51
	v_mul_f32_e32 v24, v24, v25
	v_mul_f32_e32 v28, v28, v29
	v_mul_f32_e32 v20, v20, v21
	v_mul_f32_e32 v18, v18, v22
	v_mul_f32_e32 v26, v26, v27
	v_mul_f32_e32 v30, v30, v31
	v_mul_f32_e32 v19, v19, v23
	v_cvt_pk_bf16_f32 v16, v50, v24
	v_cvt_pk_bf16_f32 v17, v28, v26
	v_cvt_pk_bf16_f32 v19, v18, v19
	v_cvt_pk_bf16_f32 v18, v30, v20
	v_mad_i64_i32 v[20:21], s[28:29], v48, s53, v[120:121]
	v_lshl_add_u64 v[20:21], v[20:21], 0, s[26:27]
	v_lshl_add_u64 v[20:21], v[20:21], 0, s[8:9]
	v_add_u32_e32 v32, 0xb0, v152
	v_lshl_add_u64 v[20:21], v[20:21], 0, v[136:137]
	v_ashrrev_i32_e32 v33, 31, v32
	global_store_dwordx4 v[20:21], v[16:19], off
	v_mov_b32_e32 v34, v12
	v_mov_b32_e32 v35, v8
	v_lshlrev_b64 v[16:17], 6, v[32:33]
	v_lshl_add_u64 v[28:29], s[74:75], 0, v[16:17]
	global_load_dwordx4 v[16:19], v[28:29], off
	global_load_dwordx4 v[20:23], v[28:29], off offset:16
	global_load_dwordx4 v[24:27], v[28:29], off offset:32
	s_nop 0
	global_load_dwordx4 v[28:31], v[28:29], off offset:48
	v_mov_b32_e32 v8, v13
	v_mov_b32_e32 v12, v14
	v_mov_b32_e32 v13, v10
	v_mov_b32_e32 v10, v15
	v_mov_b32_e32 v14, v0
	v_mov_b32_e32 v15, v4
	v_mov_b32_e32 v4, v1
	s_waitcnt vmcnt(2)
	v_pk_add_f32 v[16:17], v[16:17], v[18:19]
	v_pk_add_f32 v[20:21], v[20:21], v[22:23]
	s_waitcnt vmcnt(0)
	v_pk_add_f32 v[24:25], v[24:25], v[26:27]
	v_pk_add_f32 v[28:29], v[28:29], v[30:31]
	v_pk_add_f32 v[16:17], v[16:17], v[20:21]
	v_pk_add_f32 v[24:25], v[24:25], v[28:29]
	v_mul_f32_e32 v34, v34, v35
	v_mul_f32_e32 v8, v8, v9
	v_mul_f32_e32 v12, v12, v13
	v_mul_f32_e32 v4, v4, v5
	v_pk_add_f32 v[16:17], v[16:17], v[24:25]
	v_mul_f32_e32 v2, v2, v6
	v_mul_f32_e32 v10, v10, v11
	v_mul_f32_e32 v14, v14, v15
	v_mul_f32_e32 v3, v3, v7
	v_add_f32_e32 v16, v16, v17
	v_fmamk_f32 v16, v16, 0x3a800000, v160
	v_rsq_f32_e32 v17, v16
	s_nop 0
	v_mul_f32_e32 v17, 0xbfb8aa3b, v17
	v_mul_f32_e32 v35, v17, v35
	v_mul_f32_e32 v9, v17, v9
	v_mul_f32_e32 v13, v17, v13
	v_mul_f32_e32 v5, v17, v5
	v_mul_f32_e32 v6, v17, v6
	v_mul_f32_e32 v11, v17, v11
	v_mul_f32_e32 v15, v17, v15
	v_mul_f32_e32 v7, v17, v7
	v_exp_f32_e32 v35, v35
	v_exp_f32_e32 v9, v9
	v_exp_f32_e32 v13, v13
	v_exp_f32_e32 v5, v5
	v_exp_f32_e32 v6, v6
	v_exp_f32_e32 v11, v11
	v_exp_f32_e32 v15, v15
	v_exp_f32_e32 v7, v7
	v_fma_f32 v35, v35, v16, v16
	v_fma_f32 v9, v9, v16, v16
	v_fma_f32 v13, v13, v16, v16
	v_fma_f32 v5, v5, v16, v16
	v_fma_f32 v6, v6, v16, v16
	v_fma_f32 v11, v11, v16, v16
	v_fma_f32 v15, v15, v16, v16
	v_fma_f32 v7, v7, v16, v16
	v_rcp_f32_e32 v35, v35
	v_rcp_f32_e32 v9, v9
	v_rcp_f32_e32 v13, v13
	v_rcp_f32_e32 v5, v5
	v_rcp_f32_e32 v6, v6
	v_rcp_f32_e32 v11, v11
	v_rcp_f32_e32 v15, v15
	v_rcp_f32_e32 v7, v7
	v_mul_f32_e32 v34, v34, v35
	v_mul_f32_e32 v8, v8, v9
	v_mul_f32_e32 v12, v12, v13
	v_mul_f32_e32 v4, v4, v5
	v_mul_f32_e32 v2, v2, v6
	v_mul_f32_e32 v10, v10, v11
	v_mul_f32_e32 v14, v14, v15
	v_mul_f32_e32 v3, v3, v7
	v_cvt_pk_bf16_f32 v0, v34, v8
	v_cvt_pk_bf16_f32 v1, v12, v10
	v_cvt_pk_bf16_f32 v3, v2, v3
	v_cvt_pk_bf16_f32 v2, v14, v4
	v_mad_i64_i32 v[4:5], s[28:29], v32, s53, v[120:121]
	v_lshl_add_u64 v[4:5], v[4:5], 0, s[26:27]
	v_lshl_add_u64 v[4:5], v[4:5], 0, s[8:9]
	v_lshl_add_u64 v[4:5], v[4:5], 0, v[136:137]
	global_store_dwordx4 v[4:5], v[0:3], off
	s_andn2_b64 vcc, exec, s[4:5]
	s_mov_b64 s[4:5], -1
	s_cbranch_vccnz .LBB0_973
	s_branch .LBB0_1007

.LBB0_1135:
	v_ashrrev_i32_e32 v155, 31, v154
	v_lshlrev_b64 v[156:157], 6, v[154:155]
	v_lshl_add_u64 v[156:157], s[74:75], 0, v[156:157]
	global_load_dwordx4 v[166:169], v[156:157], off
	global_load_dwordx4 v[170:173], v[156:157], off offset:16
	global_load_dwordx4 v[174:177], v[156:157], off offset:32
	global_load_dwordx4 v[178:181], v[156:157], off offset:48
	v_mov_b32_e32 v156, v124
	v_mov_b32_e32 v157, v116
	v_mov_b32_e32 v116, v125
	v_mov_b32_e32 v124, v126
	v_mov_b32_e32 v125, v118
	v_mov_b32_e32 v118, v127
	v_mov_b32_e32 v126, v120
	v_mov_b32_e32 v127, v112
	v_mov_b32_e32 v112, v121
	v_mov_b32_e32 v182, v122
	v_mov_b32_e32 v183, v114
	v_mov_b32_e32 v114, v123
	s_lshl_b32 s28, s28, 7
	v_mov_b64_e32 v[120:121], s[72:73]
	s_ashr_i32 s29, s28, 31
	v_mad_i64_i32 v[122:123], s[30:31], v154, s54, v[120:121]
	s_lshl_b64 s[28:29], s[28:29], 1
	v_lshl_add_u64 v[122:123], v[122:123], 0, s[28:29]
	v_lshl_add_u64 v[122:123], v[122:123], 0, s[8:9]
	s_waitcnt vmcnt(2)
	v_pk_add_f32 v[166:167], v[166:167], v[168:169]
	v_pk_add_f32 v[170:171], v[170:171], v[172:173]
	s_waitcnt vmcnt(0)
	v_pk_add_f32 v[174:175], v[174:175], v[176:177]
	v_pk_add_f32 v[178:179], v[178:179], v[180:181]
	v_pk_add_f32 v[166:167], v[166:167], v[170:171]
	v_pk_add_f32 v[174:175], v[174:175], v[178:179]
	v_mul_f32_e32 v116, v116, v117
	v_mul_f32_e32 v124, v124, v125
	v_mul_f32_e32 v118, v118, v119
	v_mul_f32_e32 v126, v126, v127
	v_pk_add_f32 v[166:167], v[166:167], v[174:175]
	v_mul_f32_e32 v156, v156, v157
	v_mul_f32_e32 v112, v112, v113
	v_mul_f32_e32 v182, v182, v183
	v_mul_f32_e32 v114, v114, v115
	v_add_f32_e32 v166, v166, v167
	v_fmamk_f32 v166, v166, 0x3a800000, v163
	v_rsq_f32_e32 v167, v166
	s_nop 0
	v_mul_f32_e32 v167, 0xbfb8aa3b, v167
	v_mul_f32_e32 v117, v167, v117
	v_mul_f32_e32 v125, v167, v125
	v_mul_f32_e32 v119, v167, v119
	v_mul_f32_e32 v127, v167, v127
	v_mul_f32_e32 v157, v167, v157
	v_mul_f32_e32 v113, v167, v113
	v_mul_f32_e32 v183, v167, v183
	v_mul_f32_e32 v115, v167, v115
	v_exp_f32_e32 v117, v117
	v_exp_f32_e32 v125, v125
	v_exp_f32_e32 v119, v119
	v_exp_f32_e32 v127, v127
	v_exp_f32_e32 v157, v157
	v_exp_f32_e32 v113, v113
	v_exp_f32_e32 v183, v183
	v_exp_f32_e32 v115, v115
	v_fma_f32 v117, v117, v166, v166
	v_fma_f32 v125, v125, v166, v166
	v_fma_f32 v119, v119, v166, v166
	v_fma_f32 v127, v127, v166, v166
	v_fma_f32 v157, v157, v166, v166
	v_fma_f32 v113, v113, v166, v166
	v_fma_f32 v183, v183, v166, v166
	v_fma_f32 v115, v115, v166, v166
	v_rcp_f32_e32 v117, v117
	v_rcp_f32_e32 v125, v125
	v_rcp_f32_e32 v119, v119
	v_rcp_f32_e32 v127, v127
	v_rcp_f32_e32 v157, v157
	v_rcp_f32_e32 v113, v113
	v_rcp_f32_e32 v183, v183
	v_rcp_f32_e32 v115, v115
	v_mul_f32_e32 v116, v116, v117
	v_mul_f32_e32 v124, v124, v125
	v_mul_f32_e32 v118, v118, v119
	v_mul_f32_e32 v126, v126, v127
	v_mul_f32_e32 v156, v156, v157
	v_mul_f32_e32 v112, v112, v113
	v_mul_f32_e32 v182, v182, v183
	v_mul_f32_e32 v114, v114, v115
	v_cvt_pk_bf16_f32 v113, v124, v118
	v_cvt_pk_bf16_f32 v115, v182, v114
	v_cvt_pk_bf16_f32 v114, v126, v112
	v_cvt_pk_bf16_f32 v112, v156, v116
	v_or_b32_e32 v126, 16, v154
	v_lshl_add_u64 v[116:117], v[122:123], 0, v[136:137]
	v_ashrrev_i32_e32 v127, 31, v126
	global_store_dwordx4 v[116:117], v[112:115], off
	s_nop 1
	v_lshlrev_b64 v[112:113], 6, v[126:127]
	v_lshl_add_u64 v[156:157], s[74:75], 0, v[112:113]
	global_load_dwordx4 v[112:115], v[156:157], off
	global_load_dwordx4 v[116:119], v[156:157], off offset:16
	global_load_dwordx4 v[122:125], v[156:157], off offset:32
	global_load_dwordx4 v[166:169], v[156:157], off offset:48
	v_mov_b32_e32 v156, v108
	v_mov_b32_e32 v157, v100
	v_mov_b32_e32 v100, v109
	v_mov_b32_e32 v108, v110
	v_mov_b32_e32 v109, v102
	v_mov_b32_e32 v102, v111
	v_mov_b32_e32 v110, v104
	v_mov_b32_e32 v111, v96
	v_mov_b32_e32 v96, v105
	v_mov_b32_e32 v104, v106
	v_mov_b32_e32 v105, v98
	v_mov_b32_e32 v98, v107
	s_waitcnt vmcnt(2)
	v_pk_add_f32 v[112:113], v[112:113], v[114:115]
	v_pk_add_f32 v[116:117], v[116:117], v[118:119]
	s_waitcnt vmcnt(0)
	v_pk_add_f32 v[122:123], v[122:123], v[124:125]
	v_pk_add_f32 v[166:167], v[166:167], v[168:169]
	v_pk_add_f32 v[112:113], v[112:113], v[116:117]
	v_pk_add_f32 v[122:123], v[122:123], v[166:167]
	v_mul_f32_e32 v100, v100, v101
	v_mul_f32_e32 v108, v108, v109
	v_mul_f32_e32 v156, v156, v157
	v_mul_f32_e32 v102, v102, v103
	v_pk_add_f32 v[112:113], v[112:113], v[122:123]
	v_mul_f32_e32 v110, v110, v111
	v_mul_f32_e32 v96, v96, v97
	v_mul_f32_e32 v104, v104, v105
	v_mul_f32_e32 v98, v98, v99
	v_add_f32_e32 v112, v112, v113
	v_fmamk_f32 v112, v112, 0x3a800000, v163
	v_rsq_f32_e32 v113, v112
	s_nop 0
	v_mul_f32_e32 v113, 0xbfb8aa3b, v113
	v_mul_f32_e32 v101, v113, v101
	v_mul_f32_e32 v109, v113, v109
	v_mul_f32_e32 v157, v113, v157
	v_mul_f32_e32 v103, v113, v103
	v_mul_f32_e32 v111, v113, v111
	v_mul_f32_e32 v97, v113, v97
	v_mul_f32_e32 v105, v113, v105
	v_mul_f32_e32 v99, v113, v99
	v_exp_f32_e32 v101, v101
	v_exp_f32_e32 v109, v109
	v_exp_f32_e32 v157, v157
	v_exp_f32_e32 v103, v103
	v_exp_f32_e32 v111, v111
	v_exp_f32_e32 v97, v97
	v_exp_f32_e32 v105, v105
	v_exp_f32_e32 v99, v99
	v_fma_f32 v101, v101, v112, v112
	v_fma_f32 v109, v109, v112, v112
	v_fma_f32 v157, v157, v112, v112
	v_fma_f32 v103, v103, v112, v112
	v_fma_f32 v111, v111, v112, v112
	v_fma_f32 v97, v97, v112, v112
	v_fma_f32 v105, v105, v112, v112
	v_fma_f32 v99, v99, v112, v112
	v_rcp_f32_e32 v101, v101
	v_rcp_f32_e32 v109, v109
	v_rcp_f32_e32 v157, v157
	v_rcp_f32_e32 v103, v103
	v_rcp_f32_e32 v111, v111
	v_rcp_f32_e32 v97, v97
	v_rcp_f32_e32 v105, v105
	v_rcp_f32_e32 v99, v99
	v_mul_f32_e32 v100, v100, v101
	v_mul_f32_e32 v108, v108, v109
	v_mul_f32_e32 v156, v156, v157
	v_mul_f32_e32 v102, v102, v103
	v_mul_f32_e32 v110, v110, v111
	v_mul_f32_e32 v96, v96, v97
	v_mul_f32_e32 v104, v104, v105
	v_mul_f32_e32 v98, v98, v99
	v_cvt_pk_bf16_f32 v97, v108, v102
	v_cvt_pk_bf16_f32 v99, v104, v98
	v_cvt_pk_bf16_f32 v98, v110, v96
	v_cvt_pk_bf16_f32 v96, v156, v100
	v_mad_i64_i32 v[112:113], s[30:31], v126, s54, v[120:121]
	v_lshl_add_u64 v[112:113], v[112:113], 0, s[28:29]
	v_lshl_add_u64 v[100:101], v[112:113], 0, s[8:9]
	v_or_b32_e32 v112, 32, v154
	v_lshl_add_u64 v[100:101], v[100:101], 0, v[136:137]
	v_ashrrev_i32_e32 v113, 31, v112
	global_store_dwordx4 v[100:101], v[96:99], off
	v_mov_b32_e32 v114, v92
	v_mov_b32_e32 v92, v94
	v_lshlrev_b64 v[96:97], 6, v[112:113]
	v_lshl_add_u64 v[108:109], s[74:75], 0, v[96:97]
	global_load_dwordx4 v[96:99], v[108:109], off
	global_load_dwordx4 v[100:103], v[108:109], off offset:16
	global_load_dwordx4 v[104:107], v[108:109], off offset:32
	s_nop 0
	global_load_dwordx4 v[108:111], v[108:109], off offset:48
	v_mov_b32_e32 v94, v80
	v_mov_b32_e32 v80, v82
	v_mov_b32_e32 v115, v88
	v_mov_b32_e32 v88, v93
	v_mov_b32_e32 v93, v90
	v_mov_b32_e32 v90, v95
	v_mov_b32_e32 v95, v84
	v_mov_b32_e32 v84, v81
	v_mov_b32_e32 v81, v86
	v_mov_b32_e32 v86, v83
	s_waitcnt vmcnt(2)
	v_pk_add_f32 v[96:97], v[96:97], v[98:99]
	v_pk_add_f32 v[100:101], v[100:101], v[102:103]
	s_waitcnt vmcnt(0)
	v_pk_add_f32 v[104:105], v[104:105], v[106:107]
	v_pk_add_f32 v[108:109], v[108:109], v[110:111]
	v_pk_add_f32 v[96:97], v[96:97], v[100:101]
	v_pk_add_f32 v[104:105], v[104:105], v[108:109]
	v_mul_f32_e32 v114, v114, v115
	v_mul_f32_e32 v88, v88, v89
	v_mul_f32_e32 v92, v92, v93
	v_mul_f32_e32 v90, v90, v91
	v_pk_add_f32 v[96:97], v[96:97], v[104:105]
	v_mul_f32_e32 v94, v94, v95
	v_mul_f32_e32 v84, v84, v85
	v_mul_f32_e32 v80, v80, v81
	v_mul_f32_e32 v86, v86, v87
	v_add_f32_e32 v96, v96, v97
	v_fmamk_f32 v96, v96, 0x3a800000, v163
	v_rsq_f32_e32 v97, v96
	s_nop 0
	v_mul_f32_e32 v97, 0xbfb8aa3b, v97
	v_mul_f32_e32 v115, v97, v115
	v_mul_f32_e32 v89, v97, v89
	v_mul_f32_e32 v93, v97, v93
	v_mul_f32_e32 v91, v97, v91
	v_mul_f32_e32 v95, v97, v95
	v_mul_f32_e32 v85, v97, v85
	v_mul_f32_e32 v81, v97, v81
	v_mul_f32_e32 v87, v97, v87
	v_exp_f32_e32 v115, v115
	v_exp_f32_e32 v89, v89
	v_exp_f32_e32 v93, v93
	v_exp_f32_e32 v91, v91
	v_exp_f32_e32 v95, v95
	v_exp_f32_e32 v85, v85
	v_exp_f32_e32 v81, v81
	v_exp_f32_e32 v87, v87
	v_fma_f32 v115, v115, v96, v96
	v_fma_f32 v89, v89, v96, v96
	v_fma_f32 v93, v93, v96, v96
	v_fma_f32 v91, v91, v96, v96
	v_fma_f32 v95, v95, v96, v96
	v_fma_f32 v85, v85, v96, v96
	v_fma_f32 v81, v81, v96, v96
	v_fma_f32 v87, v87, v96, v96
	v_rcp_f32_e32 v115, v115
	v_rcp_f32_e32 v89, v89
	v_rcp_f32_e32 v93, v93
	v_rcp_f32_e32 v91, v91
	v_rcp_f32_e32 v95, v95
	v_rcp_f32_e32 v85, v85
	v_rcp_f32_e32 v81, v81
	v_rcp_f32_e32 v87, v87
	v_mul_f32_e32 v114, v114, v115
	v_mul_f32_e32 v88, v88, v89
	v_mul_f32_e32 v92, v92, v93
	v_mul_f32_e32 v90, v90, v91
	v_mul_f32_e32 v94, v94, v95
	v_mul_f32_e32 v84, v84, v85
	v_mul_f32_e32 v80, v80, v81
	v_mul_f32_e32 v86, v86, v87
	v_cvt_pk_bf16_f32 v81, v92, v90
	v_cvt_pk_bf16_f32 v82, v94, v84
	v_cvt_pk_bf16_f32 v83, v80, v86
	v_cvt_pk_bf16_f32 v80, v114, v88
	v_mad_i64_i32 v[96:97], s[30:31], v112, s54, v[120:121]
	v_lshl_add_u64 v[84:85], v[96:97], 0, s[28:29]
	v_lshl_add_u64 v[84:85], v[84:85], 0, s[8:9]
	v_or_b32_e32 v96, 48, v154
	v_lshl_add_u64 v[84:85], v[84:85], 0, v[136:137]
	v_ashrrev_i32_e32 v97, 31, v96
	global_store_dwordx4 v[84:85], v[80:83], off
	v_mov_b32_e32 v98, v76
	v_mov_b32_e32 v99, v72
	v_lshlrev_b64 v[80:81], 6, v[96:97]
	v_lshl_add_u64 v[92:93], s[74:75], 0, v[80:81]
	global_load_dwordx4 v[80:83], v[92:93], off
	global_load_dwordx4 v[84:87], v[92:93], off offset:16
	global_load_dwordx4 v[88:91], v[92:93], off offset:32
	s_nop 0
	global_load_dwordx4 v[92:95], v[92:93], off offset:48
	v_mov_b32_e32 v72, v77
	v_mov_b32_e32 v76, v78
	v_mov_b32_e32 v77, v74
	v_mov_b32_e32 v74, v79
	v_mov_b32_e32 v78, v64
	v_mov_b32_e32 v79, v68
	v_mov_b32_e32 v68, v65
	s_waitcnt vmcnt(2)
	v_pk_add_f32 v[80:81], v[80:81], v[82:83]
	v_pk_add_f32 v[84:85], v[84:85], v[86:87]
	s_waitcnt vmcnt(0)
	v_pk_add_f32 v[88:89], v[88:89], v[90:91]
	v_pk_add_f32 v[92:93], v[92:93], v[94:95]
	v_pk_add_f32 v[80:81], v[80:81], v[84:85]
	v_pk_add_f32 v[88:89], v[88:89], v[92:93]
	v_mul_f32_e32 v98, v98, v99
	v_mul_f32_e32 v72, v72, v73
	v_mul_f32_e32 v76, v76, v77
	v_mul_f32_e32 v68, v68, v69
	v_pk_add_f32 v[80:81], v[80:81], v[88:89]
	v_mul_f32_e32 v66, v66, v70
	v_mul_f32_e32 v74, v74, v75
	v_mul_f32_e32 v78, v78, v79
	v_mul_f32_e32 v67, v67, v71
	v_add_f32_e32 v80, v80, v81
	v_fmamk_f32 v80, v80, 0x3a800000, v163
	v_rsq_f32_e32 v81, v80
	s_nop 0
	v_mul_f32_e32 v81, 0xbfb8aa3b, v81
	v_mul_f32_e32 v99, v81, v99
	v_mul_f32_e32 v73, v81, v73
	v_mul_f32_e32 v77, v81, v77
	v_mul_f32_e32 v69, v81, v69
	v_mul_f32_e32 v70, v81, v70
	v_mul_f32_e32 v75, v81, v75
	v_mul_f32_e32 v79, v81, v79
	v_mul_f32_e32 v71, v81, v71
	v_exp_f32_e32 v99, v99
	v_exp_f32_e32 v73, v73
	v_exp_f32_e32 v77, v77
	v_exp_f32_e32 v69, v69
	v_exp_f32_e32 v70, v70
	v_exp_f32_e32 v75, v75
	v_exp_f32_e32 v79, v79
	v_exp_f32_e32 v71, v71
	v_fma_f32 v99, v99, v80, v80
	v_fma_f32 v73, v73, v80, v80
	v_fma_f32 v77, v77, v80, v80
	v_fma_f32 v69, v69, v80, v80
	v_fma_f32 v70, v70, v80, v80
	v_fma_f32 v75, v75, v80, v80
	v_fma_f32 v79, v79, v80, v80
	v_fma_f32 v71, v71, v80, v80
	v_rcp_f32_e32 v99, v99
	v_rcp_f32_e32 v73, v73
	v_rcp_f32_e32 v77, v77
	v_rcp_f32_e32 v69, v69
	v_rcp_f32_e32 v70, v70
	v_rcp_f32_e32 v75, v75
	v_rcp_f32_e32 v79, v79
	v_rcp_f32_e32 v71, v71
	v_mul_f32_e32 v98, v98, v99
	v_mul_f32_e32 v72, v72, v73
	v_mul_f32_e32 v76, v76, v77
	v_mul_f32_e32 v68, v68, v69
	v_mul_f32_e32 v66, v66, v70
	v_mul_f32_e32 v74, v74, v75
	v_mul_f32_e32 v78, v78, v79
	v_mul_f32_e32 v67, v67, v71
	v_cvt_pk_bf16_f32 v64, v98, v72
	v_cvt_pk_bf16_f32 v65, v76, v74
	v_cvt_pk_bf16_f32 v67, v66, v67
	v_cvt_pk_bf16_f32 v66, v78, v68
	v_mad_i64_i32 v[68:69], s[30:31], v96, s54, v[120:121]
	v_lshl_add_u64 v[68:69], v[68:69], 0, s[28:29]
	v_lshl_add_u64 v[68:69], v[68:69], 0, s[8:9]
	v_add_u32_e32 v80, 0x80, v154
	v_lshl_add_u64 v[68:69], v[68:69], 0, v[136:137]
	v_ashrrev_i32_e32 v81, 31, v80
	global_store_dwordx4 v[68:69], v[64:67], off
	v_mov_b32_e32 v82, v60
	v_mov_b32_e32 v83, v56
	v_lshlrev_b64 v[64:65], 6, v[80:81]
	v_lshl_add_u64 v[76:77], s[74:75], 0, v[64:65]
	global_load_dwordx4 v[64:67], v[76:77], off
	global_load_dwordx4 v[68:71], v[76:77], off offset:16
	global_load_dwordx4 v[72:75], v[76:77], off offset:32
	s_nop 0
	global_load_dwordx4 v[76:79], v[76:77], off offset:48
	v_mov_b32_e32 v56, v61
	v_mov_b32_e32 v60, v62
	v_mov_b32_e32 v61, v58
	v_mov_b32_e32 v58, v63
	v_mov_b32_e32 v62, v48
	v_mov_b32_e32 v63, v52
	v_mov_b32_e32 v52, v49
	s_waitcnt vmcnt(2)
	v_pk_add_f32 v[64:65], v[64:65], v[66:67]
	v_pk_add_f32 v[68:69], v[68:69], v[70:71]
	s_waitcnt vmcnt(0)
	v_pk_add_f32 v[72:73], v[72:73], v[74:75]
	v_pk_add_f32 v[76:77], v[76:77], v[78:79]
	v_pk_add_f32 v[64:65], v[64:65], v[68:69]
	v_pk_add_f32 v[72:73], v[72:73], v[76:77]
	v_mul_f32_e32 v82, v82, v83
	v_mul_f32_e32 v56, v56, v57
	v_mul_f32_e32 v60, v60, v61
	v_mul_f32_e32 v52, v52, v53
	v_pk_add_f32 v[64:65], v[64:65], v[72:73]
	v_mul_f32_e32 v50, v50, v54
	v_mul_f32_e32 v58, v58, v59
	v_mul_f32_e32 v62, v62, v63
	v_mul_f32_e32 v51, v51, v55
	v_add_f32_e32 v64, v64, v65
	v_fmamk_f32 v64, v64, 0x3a800000, v163
	v_rsq_f32_e32 v65, v64
	s_nop 0
	v_mul_f32_e32 v65, 0xbfb8aa3b, v65
	v_mul_f32_e32 v83, v65, v83
	v_mul_f32_e32 v57, v65, v57
	v_mul_f32_e32 v61, v65, v61
	v_mul_f32_e32 v53, v65, v53
	v_mul_f32_e32 v54, v65, v54
	v_mul_f32_e32 v59, v65, v59
	v_mul_f32_e32 v63, v65, v63
	v_mul_f32_e32 v55, v65, v55
	v_exp_f32_e32 v83, v83
	v_exp_f32_e32 v57, v57
	v_exp_f32_e32 v61, v61
	v_exp_f32_e32 v53, v53
	v_exp_f32_e32 v54, v54
	v_exp_f32_e32 v59, v59
	v_exp_f32_e32 v63, v63
	v_exp_f32_e32 v55, v55
	v_fma_f32 v83, v83, v64, v64
	v_fma_f32 v57, v57, v64, v64
	v_fma_f32 v61, v61, v64, v64
	v_fma_f32 v53, v53, v64, v64
	v_fma_f32 v54, v54, v64, v64
	v_fma_f32 v59, v59, v64, v64
	v_fma_f32 v63, v63, v64, v64
	v_fma_f32 v55, v55, v64, v64
	v_rcp_f32_e32 v83, v83
	v_rcp_f32_e32 v57, v57
	v_rcp_f32_e32 v61, v61
	v_rcp_f32_e32 v53, v53
	v_rcp_f32_e32 v54, v54
	v_rcp_f32_e32 v59, v59
	v_rcp_f32_e32 v63, v63
	v_rcp_f32_e32 v55, v55
	v_mul_f32_e32 v82, v82, v83
	v_mul_f32_e32 v56, v56, v57
	v_mul_f32_e32 v60, v60, v61
	v_mul_f32_e32 v52, v52, v53
	v_mul_f32_e32 v50, v50, v54
	v_mul_f32_e32 v58, v58, v59
	v_mul_f32_e32 v62, v62, v63
	v_mul_f32_e32 v51, v51, v55
	v_cvt_pk_bf16_f32 v48, v82, v56
	v_cvt_pk_bf16_f32 v49, v60, v58
	v_cvt_pk_bf16_f32 v51, v50, v51
	v_cvt_pk_bf16_f32 v50, v62, v52
	v_mad_i64_i32 v[52:53], s[30:31], v80, s54, v[120:121]
	v_lshl_add_u64 v[52:53], v[52:53], 0, s[28:29]
	v_lshl_add_u64 v[52:53], v[52:53], 0, s[8:9]
	v_add_u32_e32 v64, 0x90, v154
	v_lshl_add_u64 v[52:53], v[52:53], 0, v[136:137]
	v_ashrrev_i32_e32 v65, 31, v64
	global_store_dwordx4 v[52:53], v[48:51], off
	v_mov_b32_e32 v66, v44
	v_mov_b32_e32 v67, v40
	v_lshlrev_b64 v[48:49], 6, v[64:65]
	v_lshl_add_u64 v[60:61], s[74:75], 0, v[48:49]
	global_load_dwordx4 v[48:51], v[60:61], off
	global_load_dwordx4 v[52:55], v[60:61], off offset:16
	global_load_dwordx4 v[56:59], v[60:61], off offset:32
	s_nop 0
	global_load_dwordx4 v[60:63], v[60:61], off offset:48
	v_mov_b32_e32 v40, v45
	v_mov_b32_e32 v44, v46
	v_mov_b32_e32 v45, v42
	v_mov_b32_e32 v42, v47
	v_mov_b32_e32 v46, v32
	v_mov_b32_e32 v47, v36
	v_mov_b32_e32 v36, v33
	s_waitcnt vmcnt(2)
	v_pk_add_f32 v[48:49], v[48:49], v[50:51]
	v_pk_add_f32 v[52:53], v[52:53], v[54:55]
	s_waitcnt vmcnt(0)
	v_pk_add_f32 v[56:57], v[56:57], v[58:59]
	v_pk_add_f32 v[60:61], v[60:61], v[62:63]
	v_pk_add_f32 v[48:49], v[48:49], v[52:53]
	v_pk_add_f32 v[56:57], v[56:57], v[60:61]
	v_mul_f32_e32 v66, v66, v67
	v_mul_f32_e32 v40, v40, v41
	v_mul_f32_e32 v44, v44, v45
	v_mul_f32_e32 v36, v36, v37
	v_pk_add_f32 v[48:49], v[48:49], v[56:57]
	v_mul_f32_e32 v34, v34, v38
	v_mul_f32_e32 v42, v42, v43
	v_mul_f32_e32 v46, v46, v47
	v_mul_f32_e32 v35, v35, v39
	v_add_f32_e32 v48, v48, v49
	v_fmamk_f32 v48, v48, 0x3a800000, v163
	v_rsq_f32_e32 v49, v48
	s_nop 0
	v_mul_f32_e32 v49, 0xbfb8aa3b, v49
	v_mul_f32_e32 v67, v49, v67
	v_mul_f32_e32 v41, v49, v41
	v_mul_f32_e32 v45, v49, v45
	v_mul_f32_e32 v37, v49, v37
	v_mul_f32_e32 v38, v49, v38
	v_mul_f32_e32 v43, v49, v43
	v_mul_f32_e32 v47, v49, v47
	v_mul_f32_e32 v39, v49, v39
	v_exp_f32_e32 v67, v67
	v_exp_f32_e32 v41, v41
	v_exp_f32_e32 v45, v45
	v_exp_f32_e32 v37, v37
	v_exp_f32_e32 v38, v38
	v_exp_f32_e32 v43, v43
	v_exp_f32_e32 v47, v47
	v_exp_f32_e32 v39, v39
	v_fma_f32 v67, v67, v48, v48
	v_fma_f32 v41, v41, v48, v48
	v_fma_f32 v45, v45, v48, v48
	v_fma_f32 v37, v37, v48, v48
	v_fma_f32 v38, v38, v48, v48
	v_fma_f32 v43, v43, v48, v48
	v_fma_f32 v47, v47, v48, v48
	v_fma_f32 v39, v39, v48, v48
	v_rcp_f32_e32 v67, v67
	v_rcp_f32_e32 v41, v41
	v_rcp_f32_e32 v45, v45
	v_rcp_f32_e32 v37, v37
	v_rcp_f32_e32 v38, v38
	v_rcp_f32_e32 v43, v43
	v_rcp_f32_e32 v47, v47
	v_rcp_f32_e32 v39, v39
	v_mul_f32_e32 v66, v66, v67
	v_mul_f32_e32 v40, v40, v41
	v_mul_f32_e32 v44, v44, v45
	v_mul_f32_e32 v36, v36, v37
	v_mul_f32_e32 v34, v34, v38
	v_mul_f32_e32 v42, v42, v43
	v_mul_f32_e32 v46, v46, v47
	v_mul_f32_e32 v35, v35, v39
	v_cvt_pk_bf16_f32 v32, v66, v40
	v_cvt_pk_bf16_f32 v33, v44, v42
	v_cvt_pk_bf16_f32 v35, v34, v35
	v_cvt_pk_bf16_f32 v34, v46, v36
	v_mad_i64_i32 v[36:37], s[30:31], v64, s54, v[120:121]
	v_lshl_add_u64 v[36:37], v[36:37], 0, s[28:29]
	v_lshl_add_u64 v[36:37], v[36:37], 0, s[8:9]
	v_add_u32_e32 v48, 0xa0, v154
	v_lshl_add_u64 v[36:37], v[36:37], 0, v[136:137]
	v_ashrrev_i32_e32 v49, 31, v48
	global_store_dwordx4 v[36:37], v[32:35], off
	v_mov_b32_e32 v50, v28
	v_mov_b32_e32 v51, v24
	v_lshlrev_b64 v[32:33], 6, v[48:49]
	v_lshl_add_u64 v[44:45], s[74:75], 0, v[32:33]
	global_load_dwordx4 v[32:35], v[44:45], off
	global_load_dwordx4 v[36:39], v[44:45], off offset:16
	global_load_dwordx4 v[40:43], v[44:45], off offset:32
	s_nop 0
	global_load_dwordx4 v[44:47], v[44:45], off offset:48
	v_mov_b32_e32 v24, v29
	v_mov_b32_e32 v28, v30
	v_mov_b32_e32 v29, v26
	v_mov_b32_e32 v26, v31
	v_mov_b32_e32 v30, v16
	v_mov_b32_e32 v31, v20
	v_mov_b32_e32 v20, v17
	s_waitcnt vmcnt(2)
	v_pk_add_f32 v[32:33], v[32:33], v[34:35]
	v_pk_add_f32 v[36:37], v[36:37], v[38:39]
	s_waitcnt vmcnt(0)
	v_pk_add_f32 v[40:41], v[40:41], v[42:43]
	v_pk_add_f32 v[44:45], v[44:45], v[46:47]
	v_pk_add_f32 v[32:33], v[32:33], v[36:37]
	v_pk_add_f32 v[40:41], v[40:41], v[44:45]
	v_mul_f32_e32 v50, v50, v51
	v_mul_f32_e32 v24, v24, v25
	v_mul_f32_e32 v28, v28, v29
	v_mul_f32_e32 v20, v20, v21
	v_pk_add_f32 v[32:33], v[32:33], v[40:41]
	v_mul_f32_e32 v18, v18, v22
	v_mul_f32_e32 v26, v26, v27
	v_mul_f32_e32 v30, v30, v31
	v_mul_f32_e32 v19, v19, v23
	v_add_f32_e32 v32, v32, v33
	v_fmamk_f32 v32, v32, 0x3a800000, v163
	v_rsq_f32_e32 v33, v32
	s_nop 0
	v_mul_f32_e32 v33, 0xbfb8aa3b, v33
	v_mul_f32_e32 v51, v33, v51
	v_mul_f32_e32 v25, v33, v25
	v_mul_f32_e32 v29, v33, v29
	v_mul_f32_e32 v21, v33, v21
	v_mul_f32_e32 v22, v33, v22
	v_mul_f32_e32 v27, v33, v27
	v_mul_f32_e32 v31, v33, v31
	v_mul_f32_e32 v23, v33, v23
	v_exp_f32_e32 v51, v51
	v_exp_f32_e32 v25, v25
	v_exp_f32_e32 v29, v29
	v_exp_f32_e32 v21, v21
	v_exp_f32_e32 v22, v22
	v_exp_f32_e32 v27, v27
	v_exp_f32_e32 v31, v31
	v_exp_f32_e32 v23, v23
	v_fma_f32 v51, v51, v32, v32
	v_fma_f32 v25, v25, v32, v32
	v_fma_f32 v29, v29, v32, v32
	v_fma_f32 v21, v21, v32, v32
	v_fma_f32 v22, v22, v32, v32
	v_fma_f32 v27, v27, v32, v32
	v_fma_f32 v31, v31, v32, v32
	v_fma_f32 v23, v23, v32, v32
	v_rcp_f32_e32 v51, v51
	v_rcp_f32_e32 v25, v25
	v_rcp_f32_e32 v29, v29
	v_rcp_f32_e32 v21, v21
	v_rcp_f32_e32 v22, v22
	v_rcp_f32_e32 v27, v27
	v_rcp_f32_e32 v31, v31
	v_rcp_f32_e32 v23, v23
	v_mul_f32_e32 v50, v50, v51
	v_mul_f32_e32 v24, v24, v25
	v_mul_f32_e32 v28, v28, v29
	v_mul_f32_e32 v20, v20, v21
	v_mul_f32_e32 v18, v18, v22
	v_mul_f32_e32 v26, v26, v27
	v_mul_f32_e32 v30, v30, v31
	v_mul_f32_e32 v19, v19, v23
	v_cvt_pk_bf16_f32 v16, v50, v24
	v_cvt_pk_bf16_f32 v17, v28, v26
	v_cvt_pk_bf16_f32 v19, v18, v19
	v_cvt_pk_bf16_f32 v18, v30, v20
	v_mad_i64_i32 v[20:21], s[30:31], v48, s54, v[120:121]
	v_lshl_add_u64 v[20:21], v[20:21], 0, s[28:29]
	v_lshl_add_u64 v[20:21], v[20:21], 0, s[8:9]
	v_add_u32_e32 v32, 0xb0, v154
	v_lshl_add_u64 v[20:21], v[20:21], 0, v[136:137]
	v_ashrrev_i32_e32 v33, 31, v32
	global_store_dwordx4 v[20:21], v[16:19], off
	v_mov_b32_e32 v34, v12
	v_mov_b32_e32 v35, v8
	v_lshlrev_b64 v[16:17], 6, v[32:33]
	v_lshl_add_u64 v[28:29], s[74:75], 0, v[16:17]
	global_load_dwordx4 v[16:19], v[28:29], off
	global_load_dwordx4 v[20:23], v[28:29], off offset:16
	global_load_dwordx4 v[24:27], v[28:29], off offset:32
	s_nop 0
	global_load_dwordx4 v[28:31], v[28:29], off offset:48
	v_mov_b32_e32 v8, v13
	v_mov_b32_e32 v12, v14
	v_mov_b32_e32 v13, v10
	v_mov_b32_e32 v10, v15
	v_mov_b32_e32 v14, v0
	v_mov_b32_e32 v15, v4
	v_mov_b32_e32 v4, v1
	s_waitcnt vmcnt(2)
	v_pk_add_f32 v[16:17], v[16:17], v[18:19]
	v_pk_add_f32 v[20:21], v[20:21], v[22:23]
	s_waitcnt vmcnt(0)
	v_pk_add_f32 v[24:25], v[24:25], v[26:27]
	v_pk_add_f32 v[28:29], v[28:29], v[30:31]
	v_pk_add_f32 v[16:17], v[16:17], v[20:21]
	v_pk_add_f32 v[24:25], v[24:25], v[28:29]
	v_mul_f32_e32 v34, v34, v35
	v_mul_f32_e32 v8, v8, v9
	v_mul_f32_e32 v12, v12, v13
	v_mul_f32_e32 v4, v4, v5
	v_pk_add_f32 v[16:17], v[16:17], v[24:25]
	v_mul_f32_e32 v2, v2, v6
	v_mul_f32_e32 v10, v10, v11
	v_mul_f32_e32 v14, v14, v15
	v_mul_f32_e32 v3, v3, v7
	v_add_f32_e32 v16, v16, v17
	v_fmamk_f32 v16, v16, 0x3a800000, v163
	v_rsq_f32_e32 v17, v16
	s_nop 0
	v_mul_f32_e32 v17, 0xbfb8aa3b, v17
	v_mul_f32_e32 v35, v17, v35
	v_mul_f32_e32 v9, v17, v9
	v_mul_f32_e32 v13, v17, v13
	v_mul_f32_e32 v5, v17, v5
	v_mul_f32_e32 v6, v17, v6
	v_mul_f32_e32 v11, v17, v11
	v_mul_f32_e32 v15, v17, v15
	v_mul_f32_e32 v7, v17, v7
	v_exp_f32_e32 v35, v35
	v_exp_f32_e32 v9, v9
	v_exp_f32_e32 v13, v13
	v_exp_f32_e32 v5, v5
	v_exp_f32_e32 v6, v6
	v_exp_f32_e32 v11, v11
	v_exp_f32_e32 v15, v15
	v_exp_f32_e32 v7, v7
	v_fma_f32 v35, v35, v16, v16
	v_fma_f32 v9, v9, v16, v16
	v_fma_f32 v13, v13, v16, v16
	v_fma_f32 v5, v5, v16, v16
	v_fma_f32 v6, v6, v16, v16
	v_fma_f32 v11, v11, v16, v16
	v_fma_f32 v15, v15, v16, v16
	v_fma_f32 v7, v7, v16, v16
	v_rcp_f32_e32 v35, v35
	v_rcp_f32_e32 v9, v9
	v_rcp_f32_e32 v13, v13
	v_rcp_f32_e32 v5, v5
	v_rcp_f32_e32 v6, v6
	v_rcp_f32_e32 v11, v11
	v_rcp_f32_e32 v15, v15
	v_rcp_f32_e32 v7, v7
	v_mul_f32_e32 v34, v34, v35
	v_mul_f32_e32 v8, v8, v9
	v_mul_f32_e32 v12, v12, v13
	v_mul_f32_e32 v4, v4, v5
	v_mul_f32_e32 v2, v2, v6
	v_mul_f32_e32 v10, v10, v11
	v_mul_f32_e32 v14, v14, v15
	v_mul_f32_e32 v3, v3, v7
	v_cvt_pk_bf16_f32 v0, v34, v8
	v_cvt_pk_bf16_f32 v1, v12, v10
	v_cvt_pk_bf16_f32 v3, v2, v3
	v_cvt_pk_bf16_f32 v2, v14, v4
	v_mad_i64_i32 v[4:5], s[30:31], v32, s54, v[120:121]
	v_lshl_add_u64 v[4:5], v[4:5], 0, s[28:29]
	v_lshl_add_u64 v[4:5], v[4:5], 0, s[8:9]
	v_lshl_add_u64 v[4:5], v[4:5], 0, v[136:137]
	global_store_dwordx4 v[4:5], v[0:3], off
	s_andn2_b64 vcc, exec, s[4:5]
	s_mov_b64 s[4:5], -1
	s_cbranch_vccnz .LBB0_1127
	s_branch .LBB0_1161
